# indexer key tiles staged once per workgroup: WG-shared LDS ring, one wave DMAs each tile, one s_barrier per 8 tiles (8x less cache traffic than per-wave rings)
# baseline (speedup 1.0000x reference)
.LBB0_399:
	v_cndmask_b32_e64 v2, v159, v92, s[82:83]
	v_readlane_b32 s74, v252, 26
	v_lshlrev_b32_e32 v88, 1, v2
	v_readlane_b32 s75, v252, 27
	v_or_b32_e32 v2, v88, v95
	s_movk_i32 s80, 0x3400
	v_mov_b64_e32 v[42:43], s[74:75]
	v_readfirstlane_b32 s101, v198
	v_readfirstlane_b32 s100, v88
	s_lshr_b32 s101, s101, 6
	s_lshr_b32 vcc_lo, s100, 12
	s_and_b32 vcc_lo, vcc_lo, 1
	s_lshl_b32 vcc_lo, vcc_lo, 16
	s_lshl_b32 vcc_hi, s101, 12
	s_add_u32 vcc_hi, vcc_hi, vcc_lo
	s_mul_i32 m0, s101, 0x68000
	v_lshrrev_b32_e32 v75, 1, v93
	v_and_b32_e32 v75, 7, v75
	v_xor_b32_e32 v75, v75, v94
	v_lshlrev_b32_e32 v75, 4, v75
	v_lshl_add_u32 v75, v93, 7, v75
	v_add_u32_e32 v74, vcc_lo, v75
	v_xor_b32_e32 v75, 32, v74
	v_xor_b32_e32 v76, 64, v74
	v_xor_b32_e32 v77, 0x60, v74
	v_lshl_or_b32 v73, v94, 5, v93
	v_lshrrev_b32_e32 v72, 3, v73
	v_mul_u32_u24_e32 v72, 0x3400, v72
	v_lshrrev_b32_e32 v78, 4, v73
	v_and_b32_e32 v73, 7, v73
	v_xor_b32_e32 v73, v73, v78
	v_lshl_add_u32 v72, v73, 4, v72
	v_xor_b32_e32 v73, 64, v72
	v_and_b32_e32 v80, 0x7fe, v88
	v_lshrrev_b32_e32 v80, 5, v80
	v_mov_b32_e32 v79, s101
	v_add_u32_e32 v79, 2, v79
	s_and_b32 s100, s100, 0xf800
	s_mul_i32 s100, s100, 0x3400
	s_add_u32 s100, s100, 0xd3200
	s_add_u32 s100, s100, m0
	s_add_u32 s100, s74, s100
	s_addc_u32 s101, s75, 0
	s_mov_b32 m0, vcc_hi
	v_cmp_le_u32_e32 vcc, v79, v80
	s_and_b64 vcc, exec, vcc
	s_cbranch_vccz .Lidxd_p
	s_nop 0
	global_load_lds_dwordx4 v72, s[100:101]
	s_add_u32 m0, m0, 0x400
	s_add_u32 s100, s100, 0x1a000
	s_addc_u32 s101, s101, 0
	s_nop 0
	global_load_lds_dwordx4 v73, s[100:101]
	s_add_u32 m0, m0, 0x400
	s_add_u32 s100, s100, 0x1a000
	s_addc_u32 s101, s101, 0
	s_nop 0
	global_load_lds_dwordx4 v72, s[100:101]
	s_add_u32 m0, m0, 0x400
	s_add_u32 s100, s100, 0x1a000
	s_addc_u32 s101, s101, 0
	s_nop 0
	global_load_lds_dwordx4 v73, s[100:101]
	s_add_u32 m0, m0, 0x400
	s_add_u32 s100, s100, 0x1a000
	s_addc_u32 s101, s101, 0
	s_add_u32 m0, m0, 0x7000
	s_add_u32 s100, s100, 0x2d8000
	s_addc_u32 s101, s101, 0
	v_add_u32_e32 v79, 8, v79
	v_cmp_le_u32_e32 vcc, v79, v80
	s_and_b64 vcc, exec, vcc
	s_cbranch_vccz .Lidxd_p
	s_nop 0
	global_load_lds_dwordx4 v72, s[100:101]
	s_add_u32 m0, m0, 0x400
	s_add_u32 s100, s100, 0x1a000
	s_addc_u32 s101, s101, 0
	s_nop 0
	global_load_lds_dwordx4 v73, s[100:101]
	s_add_u32 m0, m0, 0x400
	s_add_u32 s100, s100, 0x1a000
	s_addc_u32 s101, s101, 0
	s_nop 0
	global_load_lds_dwordx4 v72, s[100:101]
	s_add_u32 m0, m0, 0x400
	s_add_u32 s100, s100, 0x1a000
	s_addc_u32 s101, s101, 0
	s_nop 0
	global_load_lds_dwordx4 v73, s[100:101]
	s_add_u32 m0, m0, 0x400
	s_add_u32 s100, s100, 0x1a000
	s_addc_u32 s101, s101, 0
	s_sub_u32 m0, m0, 0x9000
	s_add_u32 s100, s100, 0x2d8000
	s_addc_u32 s101, s101, 0
	v_add_u32_e32 v79, 8, v79
.Lidxd_p:
	v_mad_i64_i32 v[4:5], s[74:75], v2, s80, v[42:43]
	v_lshl_add_u64 v[4:5], v[4:5], 0, v[0:1]
	v_mov_b32_e32 v87, v1
	v_lshl_add_u64 v[4:5], v[4:5], 0, v[86:87]
	s_mov_b64 s[74:75], 0x1200
	v_lshl_add_u64 v[34:35], v[4:5], 0, s[74:75]
	v_add_co_u32_e32 v4, vcc, 0x1000, v4
	global_load_dwordx4 v[10:13], v[34:35], off offset:64
	s_nop 0
	v_addc_co_u32_e32 v5, vcc, 0, v5, vcc
	global_load_dwordx4 v[14:17], v[4:5], off offset:512
	v_ashrrev_i32_e32 v3, 31, v2
	v_lshlrev_b64 v[2:3], 8, v[2:3]
	v_lshl_add_u64 v[44:45], v[82:83], 0, v[2:3]
	global_load_dwordx4 v[18:21], v[44:45], off
	global_load_dwordx4 v[22:25], v[44:45], off offset:16
	global_load_dwordx4 v[26:29], v[44:45], off offset:32
	global_load_dwordx4 v[30:33], v[44:45], off offset:48
	global_load_dwordx4 v[6:9], v[34:35], off offset:32
	global_load_dwordx4 v[2:5], v[34:35], off offset:96
	s_movk_i32 s2, 0xf800
	v_and_b32_e32 v177, 0x7fe, v88
	s_waitcnt vmcnt(7)
	v_lshlrev_b32_e32 v34, 16, v10
	v_and_b32_e32 v10, 0xffff0000, v10
	v_lshlrev_b32_e32 v36, 16, v11
	v_and_b32_e32 v38, 0xffff0000, v11
	v_lshlrev_b32_e32 v40, 16, v12
	v_and_b32_e32 v12, 0xffff0000, v12
	v_lshlrev_b32_e32 v46, 16, v13
	v_and_b32_e32 v48, 0xffff0000, v13
	s_waitcnt vmcnt(6)
	v_lshlrev_b32_e32 v35, 16, v14
	v_and_b32_e32 v11, 0xffff0000, v14
	v_lshlrev_b32_e32 v37, 16, v15
	v_and_b32_e32 v39, 0xffff0000, v15
	v_lshlrev_b32_e32 v41, 16, v16
	v_and_b32_e32 v13, 0xffff0000, v16
	v_lshlrev_b32_e32 v47, 16, v17
	v_and_b32_e32 v49, 0xffff0000, v17
	s_waitcnt vmcnt(5)
	v_pk_mul_f32 v[14:15], v[18:19], v[34:35] op_sel:[0,1] op_sel_hi:[1,0]
	v_pk_mul_f32 v[16:17], v[18:19], v[34:35]
	v_pk_mul_f32 v[18:19], v[20:21], v[10:11] op_sel:[0,1] op_sel_hi:[1,0]
	v_pk_mul_f32 v[10:11], v[20:21], v[10:11]
	s_waitcnt vmcnt(4)
	v_pk_mul_f32 v[20:21], v[22:23], v[36:37] op_sel:[0,1] op_sel_hi:[1,0]
	v_pk_mul_f32 v[22:23], v[22:23], v[36:37]
	v_pk_mul_f32 v[34:35], v[24:25], v[38:39] op_sel:[0,1] op_sel_hi:[1,0]
	v_pk_mul_f32 v[24:25], v[24:25], v[38:39]
	s_waitcnt vmcnt(3)
	v_pk_mul_f32 v[36:37], v[26:27], v[40:41] op_sel:[0,1] op_sel_hi:[1,0]
	v_pk_mul_f32 v[26:27], v[26:27], v[40:41]
	v_pk_mul_f32 v[38:39], v[28:29], v[12:13] op_sel:[0,1] op_sel_hi:[1,0]
	v_pk_mul_f32 v[12:13], v[28:29], v[12:13]
	s_waitcnt vmcnt(2)
	v_pk_mul_f32 v[28:29], v[30:31], v[46:47] op_sel:[0,1] op_sel_hi:[1,0]
	v_pk_mul_f32 v[30:31], v[30:31], v[46:47]
	v_pk_mul_f32 v[40:41], v[32:33], v[48:49] op_sel:[0,1] op_sel_hi:[1,0]
	v_pk_mul_f32 v[32:33], v[32:33], v[48:49]
	v_sub_f32_e32 v14, v14, v15
	v_add_f32_e32 v15, v17, v16
	v_sub_f32_e32 v16, v18, v19
	v_add_f32_e32 v10, v10, v11
	v_sub_f32_e32 v11, v20, v21
	v_add_f32_e32 v17, v22, v23
	v_sub_f32_e32 v18, v34, v35
	v_add_f32_e32 v19, v24, v25
	v_sub_f32_e32 v20, v36, v37
	v_add_f32_e32 v21, v26, v27
	v_sub_f32_e32 v22, v38, v39
	v_add_f32_e32 v12, v12, v13
	v_sub_f32_e32 v13, v28, v29
	v_add_f32_e32 v23, v30, v31
	v_sub_f32_e32 v24, v40, v41
	v_add_f32_e32 v25, v32, v33
	v_cvt_pk_bf16_f32 v38, v14, v16
	v_cvt_pk_bf16_f32 v39, v11, v18
	v_cvt_pk_bf16_f32 v40, v20, v22
	v_cvt_pk_bf16_f32 v41, v13, v24
	v_cvt_pk_bf16_f32 v34, v15, v10
	v_cvt_pk_bf16_f32 v35, v17, v19
	v_cvt_pk_bf16_f32 v36, v21, v12
	v_cvt_pk_bf16_f32 v37, v23, v25
	global_load_dwordx4 v[10:13], v[44:45], off offset:128
	global_load_dwordx4 v[14:17], v[44:45], off offset:144
	global_load_dwordx4 v[18:21], v[44:45], off offset:160
	global_load_dwordx4 v[22:25], v[44:45], off offset:176
	v_or_b32_e32 v26, v88, v94
	v_and_or_b32 v28, v88, s2, v93
	v_mad_i64_i32 v[26:27], s[74:75], v26, s80, v[42:43]
	s_movk_i32 s2, 0x3000
	v_mad_i64_i32 v[28:29], s[74:75], v28, s80, v[42:43]
	v_add_co_u32_e32 v32, vcc, s2, v26
	v_lshl_add_u64 v[30:31], v[28:29], 0, v[86:87]
	s_nop 0
	v_addc_co_u32_e32 v33, vcc, 0, v27, vcc
	s_waitcnt vmcnt(5)
	v_lshlrev_b32_e32 v27, 16, v6
	v_and_b32_e32 v29, 0xffff0000, v6
	v_lshlrev_b32_e32 v43, 16, v7
	v_and_b32_e32 v7, 0xffff0000, v7
	v_lshlrev_b32_e32 v45, 16, v8
	v_and_b32_e32 v47, 0xffff0000, v8
	v_lshlrev_b32_e32 v49, 16, v9
	v_and_b32_e32 v9, 0xffff0000, v9
	s_waitcnt vmcnt(4)
	v_lshlrev_b32_e32 v26, 16, v2
	v_and_b32_e32 v28, 0xffff0000, v2
	v_lshlrev_b32_e32 v42, 16, v3
	v_and_b32_e32 v6, 0xffff0000, v3
	v_lshlrev_b32_e32 v44, 16, v4
	v_and_b32_e32 v46, 0xffff0000, v4
	v_and_b32_e32 v8, 0xffff0000, v5
	s_mov_b64 s[74:75], 0x3200
	v_lshlrev_b32_e32 v48, 16, v5
	v_lshl_add_u64 v[90:91], v[30:31], 0, s[74:75]
	v_add_co_u32_e32 v30, vcc, 0x3000, v30
	v_cmp_lt_u32_e64 s[74:75], 31, v177
	s_nop 0
	v_addc_co_u32_e32 v31, vcc, 0, v31, vcc
	s_waitcnt vmcnt(3)
	v_pk_mul_f32 v[2:3], v[10:11], v[26:27] op_sel:[0,1] op_sel_hi:[1,0]
	v_pk_mul_f32 v[4:5], v[10:11], v[26:27]
	v_pk_mul_f32 v[10:11], v[12:13], v[28:29] op_sel:[0,1] op_sel_hi:[1,0]
	v_pk_mul_f32 v[12:13], v[12:13], v[28:29]
	s_waitcnt vmcnt(2)
	v_pk_mul_f32 v[26:27], v[14:15], v[42:43] op_sel:[0,1] op_sel_hi:[1,0]
	v_pk_mul_f32 v[14:15], v[14:15], v[42:43]
	v_pk_mul_f32 v[28:29], v[16:17], v[6:7] op_sel:[0,1] op_sel_hi:[1,0]
	v_pk_mul_f32 v[6:7], v[16:17], v[6:7]
	s_waitcnt vmcnt(1)
	v_pk_mul_f32 v[16:17], v[18:19], v[44:45] op_sel:[0,1] op_sel_hi:[1,0]
	v_pk_mul_f32 v[18:19], v[18:19], v[44:45]
	v_pk_mul_f32 v[42:43], v[20:21], v[46:47] op_sel:[0,1] op_sel_hi:[1,0]
	v_pk_mul_f32 v[20:21], v[20:21], v[46:47]
	s_waitcnt vmcnt(0)
	v_pk_mul_f32 v[46:47], v[24:25], v[8:9] op_sel:[0,1] op_sel_hi:[1,0]
	v_pk_mul_f32 v[44:45], v[22:23], v[48:49] op_sel:[0,1] op_sel_hi:[1,0]
	v_pk_mul_f32 v[22:23], v[22:23], v[48:49]
	v_pk_mul_f32 v[8:9], v[24:25], v[8:9]
	v_sub_f32_e32 v2, v2, v3
	v_add_f32_e32 v3, v4, v5
	v_sub_f32_e32 v4, v10, v11
	v_add_f32_e32 v5, v12, v13
	v_add_f32_e32 v13, v18, v19
	v_sub_f32_e32 v18, v46, v47
	v_sub_f32_e32 v10, v26, v27
	v_add_f32_e32 v11, v14, v15
	v_sub_f32_e32 v12, v28, v29
	v_add_f32_e32 v6, v6, v7
	v_sub_f32_e32 v7, v16, v17
	v_sub_f32_e32 v14, v42, v43
	v_add_f32_e32 v15, v20, v21
	v_sub_f32_e32 v16, v44, v45
	v_add_f32_e32 v17, v22, v23
	v_add_f32_e32 v8, v8, v9
	v_cvt_pk_bf16_f32 v46, v2, v4
	v_cvt_pk_bf16_f32 v47, v10, v12
	v_cvt_pk_bf16_f32 v48, v7, v14
	v_cvt_pk_bf16_f32 v49, v16, v18
	v_cvt_pk_bf16_f32 v42, v3, v5
	v_cvt_pk_bf16_f32 v43, v11, v6
	v_cvt_pk_bf16_f32 v44, v13, v15
	v_cvt_pk_bf16_f32 v45, v17, v8
	global_load_dwordx4 v[26:29], v[90:91], off offset:32
	global_load_dwordx4 v[18:21], v[90:91], off offset:64
	global_load_dwordx4 v[2:5], v[32:33], off offset:768
	global_load_dwordx4 v[22:25], v[90:91], off offset:96
	global_load_dwordx4 v[6:9], v[30:31], off offset:512
	global_load_dwordx4 v[10:13], v[32:33], off offset:784
	s_waitcnt vmcnt(5)
	v_mov_b64_e32 v[56:57], v[28:29]
	s_waitcnt vmcnt(4)
	v_mov_b64_e32 v[52:53], v[20:21]
	v_mov_b64_e32 v[50:51], v[18:19]
	s_waitcnt vmcnt(2)
	v_mov_b64_e32 v[64:65], v[24:25]
	s_waitcnt vmcnt(1)
	v_mov_b64_e32 v[60:61], v[8:9]
	v_mov_b64_e32 v[62:63], v[22:23]
	v_mov_b64_e32 v[54:55], v[26:27]
	v_mov_b64_e32 v[58:59], v[6:7]
	s_and_saveexec_b64 s[80:81], s[74:75]
	s_cbranch_execz .LBB0_401
	v_add_co_u32_e32 v14, vcc, 0x68000, v90
	s_nop 1
	v_addc_co_u32_e32 v15, vcc, 0, v91, vcc
	global_load_dwordx4 v[58:61], v[14:15], off
	global_load_dwordx4 v[54:57], v[14:15], off offset:32
	global_load_dwordx4 v[50:53], v[14:15], off offset:64
	global_load_dwordx4 v[62:65], v[14:15], off offset:96
.LBB0_401:
	s_or_b64 exec, exec, s[80:81]
	v_lshlrev_b32_e32 v174, 16, v2
	s_waitcnt vmcnt(0)
	v_lshlrev_b32_e32 v166, 16, v10
	v_and_b32_e32 v173, 0xffff0000, v2
	v_and_b32_e32 v165, 0xffff0000, v10
	v_lshlrev_b32_e32 v172, 16, v3
	v_lshlrev_b32_e32 v164, 16, v11
	v_and_b32_e32 v171, 0xffff0000, v3
	v_and_b32_e32 v163, 0xffff0000, v11
	v_lshlrev_b32_e32 v170, 16, v4
	v_lshlrev_b32_e32 v162, 16, v12
	v_and_b32_e32 v169, 0xffff0000, v4
	v_and_b32_e32 v161, 0xffff0000, v12
	v_lshlrev_b32_e32 v168, 16, v5
	v_lshlrev_b32_e32 v160, 16, v13
	v_and_b32_e32 v167, 0xffff0000, v5
	v_and_b32_e32 v89, 0xffff0000, v13
	v_mfma_f32_32x32x16_bf16 v[2:17], v[38:41], v[6:9], 0
	v_or_b32_e32 v87, v177, v94
	v_mov_b32_e32 v175, 0
	v_mfma_f32_32x32x16_bf16 v[2:17], v[46:49], v[26:29], v[2:17]
	v_mfma_f32_32x32x16_bf16 v[2:17], v[34:37], v[18:21], v[2:17]
	v_mfma_f32_32x32x16_bf16 v[2:17], v[42:45], v[22:25], v[2:17]
	s_and_saveexec_b64 s[80:81], s[74:75]
	s_cbranch_execz .LBB0_405
	s_waitcnt lgkmcnt(0)
	s_waitcnt vmcnt(0)
	s_barrier
	v_cmp_lt_u32_e32 vcc, 63, v177
	s_and_saveexec_b64 s[74:75], vcc
	s_cbranch_execz .LBB0_404
.LBB0_404:
	s_or_b64 exec, exec, s[74:75]
	v_mfma_f32_32x32x16_bf16 v[18:33], v[38:41], v[58:61], 0
	v_mfma_f32_32x32x16_bf16 v[18:33], v[46:49], v[54:57], v[18:33]
	v_mfma_f32_32x32x16_bf16 v[18:33], v[34:37], v[50:53], v[18:33]
	v_mfma_f32_32x32x16_bf16 v[18:33], v[42:45], v[62:65], v[18:33]
	ds_read_b128 v[58:61], v74 offset:0
	ds_read_b128 v[54:57], v75 offset:0
	ds_read_b128 v[50:53], v76 offset:0
	ds_read_b128 v[62:65], v77 offset:0
	s_nop 8
	v_max_f32_e32 v18, 0, v18
	v_max_f32_e32 v19, 0, v19
	v_fma_f32 v18, v174, v18, 0
	v_max_f32_e32 v20, 0, v20
	v_fmac_f32_e32 v18, v173, v19
	v_max_f32_e32 v21, 0, v21
	v_fmac_f32_e32 v18, v172, v20
	v_max_f32_e32 v22, 0, v22
	v_fmac_f32_e32 v18, v171, v21
	v_max_f32_e32 v23, 0, v23
	v_fmac_f32_e32 v18, v170, v22
	v_max_f32_e32 v24, 0, v24
	v_fmac_f32_e32 v18, v169, v23
	v_max_f32_e32 v25, 0, v25
	v_fmac_f32_e32 v18, v168, v24
	v_max_f32_e32 v26, 0, v26
	v_fmac_f32_e32 v18, v167, v25
	v_max_f32_e32 v27, 0, v27
	v_fmac_f32_e32 v18, v166, v26
	v_max_f32_e32 v28, 0, v28
	v_fmac_f32_e32 v18, v165, v27
	v_max_f32_e32 v29, 0, v29
	v_fmac_f32_e32 v18, v164, v28
	v_max_f32_e32 v30, 0, v30
	v_fmac_f32_e32 v18, v163, v29
	v_fmac_f32_e32 v18, v162, v30
	v_max_f32_e32 v19, 0, v31
	v_fmac_f32_e32 v18, v161, v19
	v_max_f32_e32 v19, 0, v32
	v_fmac_f32_e32 v18, v160, v19
	v_max_f32_e32 v19, 0, v33
	v_fmac_f32_e32 v18, v89, v19
	v_not_b32_e32 v19, v18
	v_or_b32_e32 v20, 0x80000000, v18
	v_cmp_gt_i32_e32 vcc, 0, v18
	s_nop 1
	v_cndmask_b32_e32 v18, v20, v19, vcc
	v_cmp_le_u32_e32 vcc, v96, v87
	s_nop 1
	v_cndmask_b32_e32 v175, 0, v18, vcc

.LBB0_408:
	s_or_b64 exec, exec, s[82:83]
	v_mfma_f32_32x32x16_bf16 v[18:33], v[38:41], v[58:61], 0
	v_mfma_f32_32x32x16_bf16 v[18:33], v[46:49], v[54:57], v[18:33]
	v_mfma_f32_32x32x16_bf16 v[18:33], v[34:37], v[50:53], v[18:33]
	v_mfma_f32_32x32x16_bf16 v[18:33], v[42:45], v[62:65], v[18:33]
	ds_read_b128 v[58:61], v74 offset:4096
	ds_read_b128 v[54:57], v75 offset:4096
	ds_read_b128 v[50:53], v76 offset:4096
	ds_read_b128 v[62:65], v77 offset:4096
	s_nop 8
	v_max_f32_e32 v18, 0, v18
	v_max_f32_e32 v19, 0, v19
	v_fma_f32 v18, v174, v18, 0
	v_max_f32_e32 v20, 0, v20
	v_fmac_f32_e32 v18, v173, v19
	v_max_f32_e32 v21, 0, v21
	v_fmac_f32_e32 v18, v172, v20
	v_max_f32_e32 v22, 0, v22
	v_fmac_f32_e32 v18, v171, v21
	v_max_f32_e32 v23, 0, v23
	v_fmac_f32_e32 v18, v170, v22
	v_max_f32_e32 v24, 0, v24
	v_fmac_f32_e32 v18, v169, v23
	v_max_f32_e32 v25, 0, v25
	v_fmac_f32_e32 v18, v168, v24
	v_max_f32_e32 v26, 0, v26
	v_fmac_f32_e32 v18, v167, v25
	v_max_f32_e32 v27, 0, v27
	v_fmac_f32_e32 v18, v166, v26
	v_max_f32_e32 v28, 0, v28
	v_fmac_f32_e32 v18, v165, v27
	v_max_f32_e32 v29, 0, v29
	v_fmac_f32_e32 v18, v164, v28
	v_max_f32_e32 v30, 0, v30
	v_fmac_f32_e32 v18, v163, v29
	v_fmac_f32_e32 v18, v162, v30
	v_max_f32_e32 v19, 0, v31
	v_fmac_f32_e32 v18, v161, v19
	v_max_f32_e32 v19, 0, v32
	v_fmac_f32_e32 v18, v160, v19
	v_max_f32_e32 v19, 0, v33
	v_fmac_f32_e32 v18, v89, v19
	v_not_b32_e32 v19, v18
	v_or_b32_e32 v20, 0x80000000, v18
	v_cmp_gt_i32_e32 vcc, 0, v18
	s_nop 1
	v_cndmask_b32_e32 v18, v20, v19, vcc
	v_cmp_le_u32_e32 vcc, v97, v87
	s_nop 1
	v_cndmask_b32_e32 v176, 0, v18, vcc

.LBB0_412:
	s_or_b64 exec, exec, s[82:83]
	v_mfma_f32_32x32x16_bf16 v[18:33], v[38:41], v[58:61], 0
	v_mfma_f32_32x32x16_bf16 v[18:33], v[46:49], v[54:57], v[18:33]
	v_mfma_f32_32x32x16_bf16 v[18:33], v[34:37], v[50:53], v[18:33]
	v_mfma_f32_32x32x16_bf16 v[18:33], v[42:45], v[62:65], v[18:33]
	ds_read_b128 v[58:61], v74 offset:8192
	ds_read_b128 v[54:57], v75 offset:8192
	ds_read_b128 v[50:53], v76 offset:8192
	ds_read_b128 v[62:65], v77 offset:8192
	s_nop 8
	v_max_f32_e32 v18, 0, v18
	v_max_f32_e32 v19, 0, v19
	v_fma_f32 v18, v174, v18, 0
	v_max_f32_e32 v20, 0, v20
	v_fmac_f32_e32 v18, v173, v19
	v_max_f32_e32 v21, 0, v21
	v_fmac_f32_e32 v18, v172, v20
	v_max_f32_e32 v22, 0, v22
	v_fmac_f32_e32 v18, v171, v21
	v_max_f32_e32 v23, 0, v23
	v_fmac_f32_e32 v18, v170, v22
	v_max_f32_e32 v24, 0, v24
	v_fmac_f32_e32 v18, v169, v23
	v_max_f32_e32 v25, 0, v25
	v_fmac_f32_e32 v18, v168, v24
	v_max_f32_e32 v26, 0, v26
	v_fmac_f32_e32 v18, v167, v25
	v_max_f32_e32 v27, 0, v27
	v_fmac_f32_e32 v18, v166, v26
	v_max_f32_e32 v28, 0, v28
	v_fmac_f32_e32 v18, v165, v27
	v_max_f32_e32 v29, 0, v29
	v_fmac_f32_e32 v18, v164, v28
	v_max_f32_e32 v30, 0, v30
	v_fmac_f32_e32 v18, v163, v29
	v_fmac_f32_e32 v18, v162, v30
	v_max_f32_e32 v19, 0, v31
	v_fmac_f32_e32 v18, v161, v19
	v_max_f32_e32 v19, 0, v32
	v_fmac_f32_e32 v18, v160, v19
	v_max_f32_e32 v19, 0, v33
	v_fmac_f32_e32 v18, v89, v19
	v_not_b32_e32 v19, v18
	v_or_b32_e32 v20, 0x80000000, v18
	v_cmp_gt_i32_e32 vcc, 0, v18
	s_nop 1
	v_cndmask_b32_e32 v18, v20, v19, vcc
	v_cmp_le_u32_e32 vcc, v98, v87
	s_nop 1
	v_cndmask_b32_e32 v179, 0, v18, vcc

.LBB0_416:
	s_or_b64 exec, exec, s[82:83]
	v_mfma_f32_32x32x16_bf16 v[18:33], v[38:41], v[58:61], 0
	v_mfma_f32_32x32x16_bf16 v[18:33], v[46:49], v[54:57], v[18:33]
	v_mfma_f32_32x32x16_bf16 v[18:33], v[34:37], v[50:53], v[18:33]
	v_mfma_f32_32x32x16_bf16 v[18:33], v[42:45], v[62:65], v[18:33]
	ds_read_b128 v[58:61], v74 offset:12288
	ds_read_b128 v[54:57], v75 offset:12288
	ds_read_b128 v[50:53], v76 offset:12288
	ds_read_b128 v[62:65], v77 offset:12288
	s_nop 8
	v_max_f32_e32 v18, 0, v18
	v_max_f32_e32 v19, 0, v19
	v_fma_f32 v18, v174, v18, 0
	v_max_f32_e32 v20, 0, v20
	v_fmac_f32_e32 v18, v173, v19
	v_max_f32_e32 v21, 0, v21
	v_fmac_f32_e32 v18, v172, v20
	v_max_f32_e32 v22, 0, v22
	v_fmac_f32_e32 v18, v171, v21
	v_max_f32_e32 v23, 0, v23
	v_fmac_f32_e32 v18, v170, v22
	v_max_f32_e32 v24, 0, v24
	v_fmac_f32_e32 v18, v169, v23
	v_max_f32_e32 v25, 0, v25
	v_fmac_f32_e32 v18, v168, v24
	v_max_f32_e32 v26, 0, v26
	v_fmac_f32_e32 v18, v167, v25
	v_max_f32_e32 v27, 0, v27
	v_fmac_f32_e32 v18, v166, v26
	v_max_f32_e32 v28, 0, v28
	v_fmac_f32_e32 v18, v165, v27
	v_max_f32_e32 v29, 0, v29
	v_fmac_f32_e32 v18, v164, v28
	v_max_f32_e32 v30, 0, v30
	v_fmac_f32_e32 v18, v163, v29
	v_fmac_f32_e32 v18, v162, v30
	v_max_f32_e32 v19, 0, v31
	v_fmac_f32_e32 v18, v161, v19
	v_max_f32_e32 v19, 0, v32
	v_fmac_f32_e32 v18, v160, v19
	v_max_f32_e32 v19, 0, v33
	v_fmac_f32_e32 v18, v89, v19
	v_not_b32_e32 v19, v18
	v_or_b32_e32 v20, 0x80000000, v18
	v_cmp_gt_i32_e32 vcc, 0, v18
	s_nop 1
	v_cndmask_b32_e32 v18, v20, v19, vcc
	v_cmp_le_u32_e32 vcc, v99, v87
	s_nop 1
	v_cndmask_b32_e32 v180, 0, v18, vcc

.LBB0_420:
	s_or_b64 exec, exec, s[82:83]
	v_mfma_f32_32x32x16_bf16 v[18:33], v[38:41], v[58:61], 0
	v_mfma_f32_32x32x16_bf16 v[18:33], v[46:49], v[54:57], v[18:33]
	v_mfma_f32_32x32x16_bf16 v[18:33], v[34:37], v[50:53], v[18:33]
	v_mfma_f32_32x32x16_bf16 v[18:33], v[42:45], v[62:65], v[18:33]
	ds_read_b128 v[58:61], v74 offset:16384
	ds_read_b128 v[54:57], v75 offset:16384
	ds_read_b128 v[50:53], v76 offset:16384
	ds_read_b128 v[62:65], v77 offset:16384
	s_nop 8
	v_max_f32_e32 v18, 0, v18
	v_max_f32_e32 v19, 0, v19
	v_fma_f32 v18, v174, v18, 0
	v_max_f32_e32 v20, 0, v20
	v_fmac_f32_e32 v18, v173, v19
	v_max_f32_e32 v21, 0, v21
	v_fmac_f32_e32 v18, v172, v20
	v_max_f32_e32 v22, 0, v22
	v_fmac_f32_e32 v18, v171, v21
	v_max_f32_e32 v23, 0, v23
	v_fmac_f32_e32 v18, v170, v22
	v_max_f32_e32 v24, 0, v24
	v_fmac_f32_e32 v18, v169, v23
	v_max_f32_e32 v25, 0, v25
	v_fmac_f32_e32 v18, v168, v24
	v_max_f32_e32 v26, 0, v26
	v_fmac_f32_e32 v18, v167, v25
	v_max_f32_e32 v27, 0, v27
	v_fmac_f32_e32 v18, v166, v26
	v_max_f32_e32 v28, 0, v28
	v_fmac_f32_e32 v18, v165, v27
	v_max_f32_e32 v29, 0, v29
	v_fmac_f32_e32 v18, v164, v28
	v_max_f32_e32 v30, 0, v30
	v_fmac_f32_e32 v18, v163, v29
	v_fmac_f32_e32 v18, v162, v30
	v_max_f32_e32 v19, 0, v31
	v_fmac_f32_e32 v18, v161, v19
	v_max_f32_e32 v19, 0, v32
	v_fmac_f32_e32 v18, v160, v19
	v_max_f32_e32 v19, 0, v33
	v_fmac_f32_e32 v18, v89, v19
	v_not_b32_e32 v19, v18
	v_or_b32_e32 v20, 0x80000000, v18
	v_cmp_gt_i32_e32 vcc, 0, v18
	s_nop 1
	v_cndmask_b32_e32 v18, v20, v19, vcc
	v_cmp_le_u32_e32 vcc, v100, v87
	s_nop 1
	v_cndmask_b32_e32 v181, 0, v18, vcc

.LBB0_424:
	s_or_b64 exec, exec, s[82:83]
	v_mfma_f32_32x32x16_bf16 v[18:33], v[38:41], v[58:61], 0
	v_mfma_f32_32x32x16_bf16 v[18:33], v[46:49], v[54:57], v[18:33]
	v_mfma_f32_32x32x16_bf16 v[18:33], v[34:37], v[50:53], v[18:33]
	v_mfma_f32_32x32x16_bf16 v[18:33], v[42:45], v[62:65], v[18:33]
	ds_read_b128 v[58:61], v74 offset:20480
	ds_read_b128 v[54:57], v75 offset:20480
	ds_read_b128 v[50:53], v76 offset:20480
	ds_read_b128 v[62:65], v77 offset:20480
	s_nop 8
	v_max_f32_e32 v18, 0, v18
	v_max_f32_e32 v19, 0, v19
	v_fma_f32 v18, v174, v18, 0
	v_max_f32_e32 v20, 0, v20
	v_fmac_f32_e32 v18, v173, v19
	v_max_f32_e32 v21, 0, v21
	v_fmac_f32_e32 v18, v172, v20
	v_max_f32_e32 v22, 0, v22
	v_fmac_f32_e32 v18, v171, v21
	v_max_f32_e32 v23, 0, v23
	v_fmac_f32_e32 v18, v170, v22
	v_max_f32_e32 v24, 0, v24
	v_fmac_f32_e32 v18, v169, v23
	v_max_f32_e32 v25, 0, v25
	v_fmac_f32_e32 v18, v168, v24
	v_max_f32_e32 v26, 0, v26
	v_fmac_f32_e32 v18, v167, v25
	v_max_f32_e32 v27, 0, v27
	v_fmac_f32_e32 v18, v166, v26
	v_max_f32_e32 v28, 0, v28
	v_fmac_f32_e32 v18, v165, v27
	v_max_f32_e32 v29, 0, v29
	v_fmac_f32_e32 v18, v164, v28
	v_max_f32_e32 v30, 0, v30
	v_fmac_f32_e32 v18, v163, v29
	v_fmac_f32_e32 v18, v162, v30
	v_max_f32_e32 v19, 0, v31
	v_fmac_f32_e32 v18, v161, v19
	v_max_f32_e32 v19, 0, v32
	v_fmac_f32_e32 v18, v160, v19
	v_max_f32_e32 v19, 0, v33
	v_fmac_f32_e32 v18, v89, v19
	v_not_b32_e32 v19, v18
	v_or_b32_e32 v20, 0x80000000, v18
	v_cmp_gt_i32_e32 vcc, 0, v18
	s_nop 1
	v_cndmask_b32_e32 v18, v20, v19, vcc
	v_cmp_le_u32_e32 vcc, v101, v87
	s_nop 1
	v_cndmask_b32_e32 v182, 0, v18, vcc

.LBB0_428:
	s_or_b64 exec, exec, s[82:83]
	v_mfma_f32_32x32x16_bf16 v[18:33], v[38:41], v[58:61], 0
	v_mfma_f32_32x32x16_bf16 v[18:33], v[46:49], v[54:57], v[18:33]
	v_mfma_f32_32x32x16_bf16 v[18:33], v[34:37], v[50:53], v[18:33]
	v_mfma_f32_32x32x16_bf16 v[18:33], v[42:45], v[62:65], v[18:33]
	ds_read_b128 v[58:61], v74 offset:24576
	ds_read_b128 v[54:57], v75 offset:24576
	ds_read_b128 v[50:53], v76 offset:24576
	ds_read_b128 v[62:65], v77 offset:24576
	s_nop 8
	v_max_f32_e32 v18, 0, v18
	v_max_f32_e32 v19, 0, v19
	v_fma_f32 v18, v174, v18, 0
	v_max_f32_e32 v20, 0, v20
	v_fmac_f32_e32 v18, v173, v19
	v_max_f32_e32 v21, 0, v21
	v_fmac_f32_e32 v18, v172, v20
	v_max_f32_e32 v22, 0, v22
	v_fmac_f32_e32 v18, v171, v21
	v_max_f32_e32 v23, 0, v23
	v_fmac_f32_e32 v18, v170, v22
	v_max_f32_e32 v24, 0, v24
	v_fmac_f32_e32 v18, v169, v23
	v_max_f32_e32 v25, 0, v25
	v_fmac_f32_e32 v18, v168, v24
	v_max_f32_e32 v26, 0, v26
	v_fmac_f32_e32 v18, v167, v25
	v_max_f32_e32 v27, 0, v27
	v_fmac_f32_e32 v18, v166, v26
	v_max_f32_e32 v28, 0, v28
	v_fmac_f32_e32 v18, v165, v27
	v_max_f32_e32 v29, 0, v29
	v_fmac_f32_e32 v18, v164, v28
	v_max_f32_e32 v30, 0, v30
	v_fmac_f32_e32 v18, v163, v29
	v_fmac_f32_e32 v18, v162, v30
	v_max_f32_e32 v19, 0, v31
	v_fmac_f32_e32 v18, v161, v19
	v_max_f32_e32 v19, 0, v32
	v_fmac_f32_e32 v18, v160, v19
	v_max_f32_e32 v19, 0, v33
	v_fmac_f32_e32 v18, v89, v19
	v_not_b32_e32 v19, v18
	v_or_b32_e32 v20, 0x80000000, v18
	v_cmp_gt_i32_e32 vcc, 0, v18
	s_nop 1
	v_cndmask_b32_e32 v18, v20, v19, vcc
	v_cmp_le_u32_e32 vcc, v102, v87
	s_nop 1
	v_cndmask_b32_e32 v183, 0, v18, vcc

.LBB0_432:
	s_or_b64 exec, exec, s[84:85]
	v_mfma_f32_32x32x16_bf16 v[18:33], v[38:41], v[58:61], 0
	v_mfma_f32_32x32x16_bf16 v[18:33], v[46:49], v[54:57], v[18:33]
	v_mfma_f32_32x32x16_bf16 v[18:33], v[34:37], v[50:53], v[18:33]
	v_mfma_f32_32x32x16_bf16 v[18:33], v[42:45], v[62:65], v[18:33]
	ds_read_b128 v[58:61], v74 offset:28672
	ds_read_b128 v[54:57], v75 offset:28672
	ds_read_b128 v[50:53], v76 offset:28672
	ds_read_b128 v[62:65], v77 offset:28672
	s_nop 8
	v_max_f32_e32 v18, 0, v18
	v_max_f32_e32 v19, 0, v19
	v_fma_f32 v18, v174, v18, 0
	v_max_f32_e32 v20, 0, v20
	v_fmac_f32_e32 v18, v173, v19
	v_max_f32_e32 v21, 0, v21
	v_fmac_f32_e32 v18, v172, v20
	v_max_f32_e32 v22, 0, v22
	v_fmac_f32_e32 v18, v171, v21
	v_max_f32_e32 v23, 0, v23
	v_fmac_f32_e32 v18, v170, v22
	v_max_f32_e32 v24, 0, v24
	v_fmac_f32_e32 v18, v169, v23
	v_max_f32_e32 v25, 0, v25
	v_fmac_f32_e32 v18, v168, v24
	v_max_f32_e32 v26, 0, v26
	v_fmac_f32_e32 v18, v167, v25
	v_max_f32_e32 v27, 0, v27
	v_fmac_f32_e32 v18, v166, v26
	v_max_f32_e32 v28, 0, v28
	v_fmac_f32_e32 v18, v165, v27
	v_max_f32_e32 v29, 0, v29
	v_fmac_f32_e32 v18, v164, v28
	v_max_f32_e32 v30, 0, v30
	v_fmac_f32_e32 v18, v163, v29
	v_fmac_f32_e32 v18, v162, v30
	v_max_f32_e32 v19, 0, v31
	v_fmac_f32_e32 v18, v161, v19
	v_max_f32_e32 v19, 0, v32
	v_fmac_f32_e32 v18, v160, v19
	v_max_f32_e32 v19, 0, v33
	v_fmac_f32_e32 v18, v89, v19
	v_not_b32_e32 v19, v18
	v_or_b32_e32 v20, 0x80000000, v18
	v_cmp_gt_i32_e32 vcc, 0, v18
	s_nop 1
	v_cndmask_b32_e32 v18, v20, v19, vcc
	v_cmp_le_u32_e32 vcc, v103, v87
	s_nop 1
	v_cndmask_b32_e32 v184, 0, v18, vcc
.LBB0_433:
	s_or_b64 exec, exec, s[82:83]
	s_movk_i32 s2, 0x11f
	v_cmp_lt_u32_e32 vcc, s2, v177
	v_mov_b32_e32 v185, 0
	s_and_saveexec_b64 s[82:83], vcc
	s_cbranch_execz .LBB0_437
	s_movk_i32 s2, 0x13f
	s_waitcnt lgkmcnt(0)
	s_waitcnt vmcnt(0)
	s_barrier
	v_cmp_le_u32_e32 vcc, v79, v80
	s_and_b64 vcc, exec, vcc
	s_cbranch_vccz .Lidxd_s1
	s_nop 0
	global_load_lds_dwordx4 v72, s[100:101]
	s_add_u32 m0, m0, 0x400
	s_add_u32 s100, s100, 0x1a000
	s_addc_u32 s101, s101, 0
	s_nop 0
	global_load_lds_dwordx4 v73, s[100:101]
	s_add_u32 m0, m0, 0x400
	s_add_u32 s100, s100, 0x1a000
	s_addc_u32 s101, s101, 0
	s_nop 0
	global_load_lds_dwordx4 v72, s[100:101]
	s_add_u32 m0, m0, 0x400
	s_add_u32 s100, s100, 0x1a000
	s_addc_u32 s101, s101, 0
	s_nop 0
	global_load_lds_dwordx4 v73, s[100:101]
	s_add_u32 m0, m0, 0x400
	s_add_u32 s100, s100, 0x1a000
	s_addc_u32 s101, s101, 0
	s_add_u32 m0, m0, 0x7000
	s_add_u32 s100, s100, 0x2d8000
	s_addc_u32 s101, s101, 0
	v_add_u32_e32 v79, 8, v79
.Lidxd_s1:
	v_cmp_lt_u32_e32 vcc, s2, v177
	s_and_saveexec_b64 s[84:85], vcc
	s_cbranch_execz .LBB0_436
.LBB0_436:
	s_or_b64 exec, exec, s[84:85]
	v_mfma_f32_32x32x16_bf16 v[18:33], v[38:41], v[58:61], 0
	v_mfma_f32_32x32x16_bf16 v[18:33], v[46:49], v[54:57], v[18:33]
	v_mfma_f32_32x32x16_bf16 v[18:33], v[34:37], v[50:53], v[18:33]
	v_mfma_f32_32x32x16_bf16 v[18:33], v[42:45], v[62:65], v[18:33]
	ds_read_b128 v[58:61], v74 offset:32768
	ds_read_b128 v[54:57], v75 offset:32768
	ds_read_b128 v[50:53], v76 offset:32768
	ds_read_b128 v[62:65], v77 offset:32768
	s_nop 8
	v_max_f32_e32 v18, 0, v18
	v_max_f32_e32 v19, 0, v19
	v_fma_f32 v18, v174, v18, 0
	v_max_f32_e32 v20, 0, v20
	v_fmac_f32_e32 v18, v173, v19
	v_max_f32_e32 v21, 0, v21
	v_fmac_f32_e32 v18, v172, v20
	v_max_f32_e32 v22, 0, v22
	v_fmac_f32_e32 v18, v171, v21
	v_max_f32_e32 v23, 0, v23
	v_fmac_f32_e32 v18, v170, v22
	v_max_f32_e32 v24, 0, v24
	v_fmac_f32_e32 v18, v169, v23
	v_max_f32_e32 v25, 0, v25
	v_fmac_f32_e32 v18, v168, v24
	v_max_f32_e32 v26, 0, v26
	v_fmac_f32_e32 v18, v167, v25
	v_max_f32_e32 v27, 0, v27
	v_fmac_f32_e32 v18, v166, v26
	v_max_f32_e32 v28, 0, v28
	v_fmac_f32_e32 v18, v165, v27
	v_max_f32_e32 v29, 0, v29
	v_fmac_f32_e32 v18, v164, v28
	v_max_f32_e32 v30, 0, v30
	v_fmac_f32_e32 v18, v163, v29
	v_fmac_f32_e32 v18, v162, v30
	v_max_f32_e32 v19, 0, v31
	v_fmac_f32_e32 v18, v161, v19
	v_max_f32_e32 v19, 0, v32
	v_fmac_f32_e32 v18, v160, v19
	v_max_f32_e32 v19, 0, v33
	v_fmac_f32_e32 v18, v89, v19
	v_not_b32_e32 v19, v18
	v_or_b32_e32 v20, 0x80000000, v18
	v_cmp_gt_i32_e32 vcc, 0, v18
	s_nop 1
	v_cndmask_b32_e32 v18, v20, v19, vcc
	v_cmp_le_u32_e32 vcc, v104, v87
	s_nop 1
	v_cndmask_b32_e32 v185, 0, v18, vcc

.LBB0_440:
	s_or_b64 exec, exec, s[84:85]
	v_mfma_f32_32x32x16_bf16 v[18:33], v[38:41], v[58:61], 0
	v_mfma_f32_32x32x16_bf16 v[18:33], v[46:49], v[54:57], v[18:33]
	v_mfma_f32_32x32x16_bf16 v[18:33], v[34:37], v[50:53], v[18:33]
	v_mfma_f32_32x32x16_bf16 v[18:33], v[42:45], v[62:65], v[18:33]
	ds_read_b128 v[58:61], v74 offset:36864
	ds_read_b128 v[54:57], v75 offset:36864
	ds_read_b128 v[50:53], v76 offset:36864
	ds_read_b128 v[62:65], v77 offset:36864
	s_nop 8
	v_max_f32_e32 v18, 0, v18
	v_max_f32_e32 v19, 0, v19
	v_fma_f32 v18, v174, v18, 0
	v_max_f32_e32 v20, 0, v20
	v_fmac_f32_e32 v18, v173, v19
	v_max_f32_e32 v21, 0, v21
	v_fmac_f32_e32 v18, v172, v20
	v_max_f32_e32 v22, 0, v22
	v_fmac_f32_e32 v18, v171, v21
	v_max_f32_e32 v23, 0, v23
	v_fmac_f32_e32 v18, v170, v22
	v_max_f32_e32 v24, 0, v24
	v_fmac_f32_e32 v18, v169, v23
	v_max_f32_e32 v25, 0, v25
	v_fmac_f32_e32 v18, v168, v24
	v_max_f32_e32 v26, 0, v26
	v_fmac_f32_e32 v18, v167, v25
	v_max_f32_e32 v27, 0, v27
	v_fmac_f32_e32 v18, v166, v26
	v_max_f32_e32 v28, 0, v28
	v_fmac_f32_e32 v18, v165, v27
	v_max_f32_e32 v29, 0, v29
	v_fmac_f32_e32 v18, v164, v28
	v_max_f32_e32 v30, 0, v30
	v_fmac_f32_e32 v18, v163, v29
	v_fmac_f32_e32 v18, v162, v30
	v_max_f32_e32 v19, 0, v31
	v_fmac_f32_e32 v18, v161, v19
	v_max_f32_e32 v19, 0, v32
	v_fmac_f32_e32 v18, v160, v19
	v_max_f32_e32 v19, 0, v33
	v_fmac_f32_e32 v18, v89, v19
	v_not_b32_e32 v19, v18
	v_or_b32_e32 v20, 0x80000000, v18
	v_cmp_gt_i32_e32 vcc, 0, v18
	s_nop 1
	v_cndmask_b32_e32 v18, v20, v19, vcc
	v_cmp_le_u32_e32 vcc, v105, v87
	s_nop 1
	v_cndmask_b32_e32 v186, 0, v18, vcc

.LBB0_444:
	s_or_b64 exec, exec, s[84:85]
	v_mfma_f32_32x32x16_bf16 v[18:33], v[38:41], v[58:61], 0
	v_mfma_f32_32x32x16_bf16 v[18:33], v[46:49], v[54:57], v[18:33]
	v_mfma_f32_32x32x16_bf16 v[18:33], v[34:37], v[50:53], v[18:33]
	v_mfma_f32_32x32x16_bf16 v[18:33], v[42:45], v[62:65], v[18:33]
	ds_read_b128 v[58:61], v74 offset:40960
	ds_read_b128 v[54:57], v75 offset:40960
	ds_read_b128 v[50:53], v76 offset:40960
	ds_read_b128 v[62:65], v77 offset:40960
	s_nop 8
	v_max_f32_e32 v18, 0, v18
	v_max_f32_e32 v19, 0, v19
	v_fma_f32 v18, v174, v18, 0
	v_max_f32_e32 v20, 0, v20
	v_fmac_f32_e32 v18, v173, v19
	v_max_f32_e32 v21, 0, v21
	v_fmac_f32_e32 v18, v172, v20
	v_max_f32_e32 v22, 0, v22
	v_fmac_f32_e32 v18, v171, v21
	v_max_f32_e32 v23, 0, v23
	v_fmac_f32_e32 v18, v170, v22
	v_max_f32_e32 v24, 0, v24
	v_fmac_f32_e32 v18, v169, v23
	v_max_f32_e32 v25, 0, v25
	v_fmac_f32_e32 v18, v168, v24
	v_max_f32_e32 v26, 0, v26
	v_fmac_f32_e32 v18, v167, v25
	v_max_f32_e32 v27, 0, v27
	v_fmac_f32_e32 v18, v166, v26
	v_max_f32_e32 v28, 0, v28
	v_fmac_f32_e32 v18, v165, v27
	v_max_f32_e32 v29, 0, v29
	v_fmac_f32_e32 v18, v164, v28
	v_max_f32_e32 v30, 0, v30
	v_fmac_f32_e32 v18, v163, v29
	v_fmac_f32_e32 v18, v162, v30
	v_max_f32_e32 v19, 0, v31
	v_fmac_f32_e32 v18, v161, v19
	v_max_f32_e32 v19, 0, v32
	v_fmac_f32_e32 v18, v160, v19
	v_max_f32_e32 v19, 0, v33
	v_fmac_f32_e32 v18, v89, v19
	v_not_b32_e32 v19, v18
	v_or_b32_e32 v20, 0x80000000, v18
	v_cmp_gt_i32_e32 vcc, 0, v18
	s_nop 1
	v_cndmask_b32_e32 v18, v20, v19, vcc
	v_cmp_le_u32_e32 vcc, v106, v87
	s_nop 1
	v_cndmask_b32_e32 v187, 0, v18, vcc

.LBB0_448:
	s_or_b64 exec, exec, s[84:85]
	v_mfma_f32_32x32x16_bf16 v[18:33], v[38:41], v[58:61], 0
	v_mfma_f32_32x32x16_bf16 v[18:33], v[46:49], v[54:57], v[18:33]
	v_mfma_f32_32x32x16_bf16 v[18:33], v[34:37], v[50:53], v[18:33]
	v_mfma_f32_32x32x16_bf16 v[18:33], v[42:45], v[62:65], v[18:33]
	ds_read_b128 v[58:61], v74 offset:45056
	ds_read_b128 v[54:57], v75 offset:45056
	ds_read_b128 v[50:53], v76 offset:45056
	ds_read_b128 v[62:65], v77 offset:45056
	s_nop 8
	v_max_f32_e32 v18, 0, v18
	v_max_f32_e32 v19, 0, v19
	v_fma_f32 v18, v174, v18, 0
	v_max_f32_e32 v20, 0, v20
	v_fmac_f32_e32 v18, v173, v19
	v_max_f32_e32 v21, 0, v21
	v_fmac_f32_e32 v18, v172, v20
	v_max_f32_e32 v22, 0, v22
	v_fmac_f32_e32 v18, v171, v21
	v_max_f32_e32 v23, 0, v23
	v_fmac_f32_e32 v18, v170, v22
	v_max_f32_e32 v24, 0, v24
	v_fmac_f32_e32 v18, v169, v23
	v_max_f32_e32 v25, 0, v25
	v_fmac_f32_e32 v18, v168, v24
	v_max_f32_e32 v26, 0, v26
	v_fmac_f32_e32 v18, v167, v25
	v_max_f32_e32 v27, 0, v27
	v_fmac_f32_e32 v18, v166, v26
	v_max_f32_e32 v28, 0, v28
	v_fmac_f32_e32 v18, v165, v27
	v_max_f32_e32 v29, 0, v29
	v_fmac_f32_e32 v18, v164, v28
	v_max_f32_e32 v30, 0, v30
	v_fmac_f32_e32 v18, v163, v29
	v_fmac_f32_e32 v18, v162, v30
	v_max_f32_e32 v19, 0, v31
	v_fmac_f32_e32 v18, v161, v19
	v_max_f32_e32 v19, 0, v32
	v_fmac_f32_e32 v18, v160, v19
	v_max_f32_e32 v19, 0, v33
	v_fmac_f32_e32 v18, v89, v19
	v_not_b32_e32 v19, v18
	v_or_b32_e32 v20, 0x80000000, v18
	v_cmp_gt_i32_e32 vcc, 0, v18
	s_nop 1
	v_cndmask_b32_e32 v18, v20, v19, vcc
	v_cmp_le_u32_e32 vcc, v107, v87
	s_nop 1
	v_cndmask_b32_e32 v188, 0, v18, vcc

.LBB0_452:
	s_or_b64 exec, exec, s[84:85]
	v_mfma_f32_32x32x16_bf16 v[18:33], v[38:41], v[58:61], 0
	v_mfma_f32_32x32x16_bf16 v[18:33], v[46:49], v[54:57], v[18:33]
	v_mfma_f32_32x32x16_bf16 v[18:33], v[34:37], v[50:53], v[18:33]
	v_mfma_f32_32x32x16_bf16 v[18:33], v[42:45], v[62:65], v[18:33]
	ds_read_b128 v[58:61], v74 offset:49152
	ds_read_b128 v[54:57], v75 offset:49152
	ds_read_b128 v[50:53], v76 offset:49152
	ds_read_b128 v[62:65], v77 offset:49152
	s_nop 8
	v_max_f32_e32 v18, 0, v18
	v_max_f32_e32 v19, 0, v19
	v_fma_f32 v18, v174, v18, 0
	v_max_f32_e32 v20, 0, v20
	v_fmac_f32_e32 v18, v173, v19
	v_max_f32_e32 v21, 0, v21
	v_fmac_f32_e32 v18, v172, v20
	v_max_f32_e32 v22, 0, v22
	v_fmac_f32_e32 v18, v171, v21
	v_max_f32_e32 v23, 0, v23
	v_fmac_f32_e32 v18, v170, v22
	v_max_f32_e32 v24, 0, v24
	v_fmac_f32_e32 v18, v169, v23
	v_max_f32_e32 v25, 0, v25
	v_fmac_f32_e32 v18, v168, v24
	v_max_f32_e32 v26, 0, v26
	v_fmac_f32_e32 v18, v167, v25
	v_max_f32_e32 v27, 0, v27
	v_fmac_f32_e32 v18, v166, v26
	v_max_f32_e32 v28, 0, v28
	v_fmac_f32_e32 v18, v165, v27
	v_max_f32_e32 v29, 0, v29
	v_fmac_f32_e32 v18, v164, v28
	v_max_f32_e32 v30, 0, v30
	v_fmac_f32_e32 v18, v163, v29
	v_fmac_f32_e32 v18, v162, v30
	v_max_f32_e32 v19, 0, v31
	v_fmac_f32_e32 v18, v161, v19
	v_max_f32_e32 v19, 0, v32
	v_fmac_f32_e32 v18, v160, v19
	v_max_f32_e32 v19, 0, v33
	v_fmac_f32_e32 v18, v89, v19
	v_not_b32_e32 v19, v18
	v_or_b32_e32 v20, 0x80000000, v18
	v_cmp_gt_i32_e32 vcc, 0, v18
	s_nop 1
	v_cndmask_b32_e32 v18, v20, v19, vcc
	v_cmp_le_u32_e32 vcc, v108, v87
	s_nop 1
	v_cndmask_b32_e32 v189, 0, v18, vcc

.LBB0_456:
	s_or_b64 exec, exec, s[84:85]
	v_mfma_f32_32x32x16_bf16 v[18:33], v[38:41], v[58:61], 0
	v_mfma_f32_32x32x16_bf16 v[18:33], v[46:49], v[54:57], v[18:33]
	v_mfma_f32_32x32x16_bf16 v[18:33], v[34:37], v[50:53], v[18:33]
	v_mfma_f32_32x32x16_bf16 v[18:33], v[42:45], v[62:65], v[18:33]
	ds_read_b128 v[58:61], v74 offset:53248
	ds_read_b128 v[54:57], v75 offset:53248
	ds_read_b128 v[50:53], v76 offset:53248
	ds_read_b128 v[62:65], v77 offset:53248
	s_nop 8
	v_max_f32_e32 v18, 0, v18
	v_max_f32_e32 v19, 0, v19
	v_fma_f32 v18, v174, v18, 0
	v_max_f32_e32 v20, 0, v20
	v_fmac_f32_e32 v18, v173, v19
	v_max_f32_e32 v21, 0, v21
	v_fmac_f32_e32 v18, v172, v20
	v_max_f32_e32 v22, 0, v22
	v_fmac_f32_e32 v18, v171, v21
	v_max_f32_e32 v23, 0, v23
	v_fmac_f32_e32 v18, v170, v22
	v_max_f32_e32 v24, 0, v24
	v_fmac_f32_e32 v18, v169, v23
	v_max_f32_e32 v25, 0, v25
	v_fmac_f32_e32 v18, v168, v24
	v_max_f32_e32 v26, 0, v26
	v_fmac_f32_e32 v18, v167, v25
	v_max_f32_e32 v27, 0, v27
	v_fmac_f32_e32 v18, v166, v26
	v_max_f32_e32 v28, 0, v28
	v_fmac_f32_e32 v18, v165, v27
	v_max_f32_e32 v29, 0, v29
	v_fmac_f32_e32 v18, v164, v28
	v_max_f32_e32 v30, 0, v30
	v_fmac_f32_e32 v18, v163, v29
	v_fmac_f32_e32 v18, v162, v30
	v_max_f32_e32 v19, 0, v31
	v_fmac_f32_e32 v18, v161, v19
	v_max_f32_e32 v19, 0, v32
	v_fmac_f32_e32 v18, v160, v19
	v_max_f32_e32 v19, 0, v33
	v_fmac_f32_e32 v18, v89, v19
	v_not_b32_e32 v19, v18
	v_or_b32_e32 v20, 0x80000000, v18
	v_cmp_gt_i32_e32 vcc, 0, v18
	s_nop 1
	v_cndmask_b32_e32 v18, v20, v19, vcc
	v_cmp_le_u32_e32 vcc, v109, v87
	s_nop 1
	v_cndmask_b32_e32 v190, 0, v18, vcc

.LBB0_460:
	s_or_b64 exec, exec, s[84:85]
	v_mfma_f32_32x32x16_bf16 v[18:33], v[38:41], v[58:61], 0
	v_mfma_f32_32x32x16_bf16 v[18:33], v[46:49], v[54:57], v[18:33]
	v_mfma_f32_32x32x16_bf16 v[18:33], v[34:37], v[50:53], v[18:33]
	v_mfma_f32_32x32x16_bf16 v[18:33], v[42:45], v[62:65], v[18:33]
	ds_read_b128 v[58:61], v74 offset:57344
	ds_read_b128 v[54:57], v75 offset:57344
	ds_read_b128 v[50:53], v76 offset:57344
	ds_read_b128 v[62:65], v77 offset:57344
	s_nop 8
	v_max_f32_e32 v18, 0, v18
	v_max_f32_e32 v19, 0, v19
	v_fma_f32 v18, v174, v18, 0
	v_max_f32_e32 v20, 0, v20
	v_fmac_f32_e32 v18, v173, v19
	v_max_f32_e32 v21, 0, v21
	v_fmac_f32_e32 v18, v172, v20
	v_max_f32_e32 v22, 0, v22
	v_fmac_f32_e32 v18, v171, v21
	v_max_f32_e32 v23, 0, v23
	v_fmac_f32_e32 v18, v170, v22
	v_max_f32_e32 v24, 0, v24
	v_fmac_f32_e32 v18, v169, v23
	v_max_f32_e32 v25, 0, v25
	v_fmac_f32_e32 v18, v168, v24
	v_max_f32_e32 v26, 0, v26
	v_fmac_f32_e32 v18, v167, v25
	v_max_f32_e32 v27, 0, v27
	v_fmac_f32_e32 v18, v166, v26
	v_max_f32_e32 v28, 0, v28
	v_fmac_f32_e32 v18, v165, v27
	v_max_f32_e32 v29, 0, v29
	v_fmac_f32_e32 v18, v164, v28
	v_max_f32_e32 v30, 0, v30
	v_fmac_f32_e32 v18, v163, v29
	v_fmac_f32_e32 v18, v162, v30
	v_max_f32_e32 v19, 0, v31
	v_fmac_f32_e32 v18, v161, v19
	v_max_f32_e32 v19, 0, v32
	v_fmac_f32_e32 v18, v160, v19
	v_max_f32_e32 v19, 0, v33
	v_fmac_f32_e32 v18, v89, v19
	v_not_b32_e32 v19, v18
	v_or_b32_e32 v20, 0x80000000, v18
	v_cmp_gt_i32_e32 vcc, 0, v18
	s_nop 1
	v_cndmask_b32_e32 v18, v20, v19, vcc
	v_cmp_le_u32_e32 vcc, v110, v87
	s_nop 1
	v_cndmask_b32_e32 v191, 0, v18, vcc

.LBB0_464:
	s_or_b64 exec, exec, s[84:85]
	v_mfma_f32_32x32x16_bf16 v[18:33], v[38:41], v[58:61], 0
	v_mfma_f32_32x32x16_bf16 v[18:33], v[46:49], v[54:57], v[18:33]
	v_mfma_f32_32x32x16_bf16 v[18:33], v[34:37], v[50:53], v[18:33]
	v_mfma_f32_32x32x16_bf16 v[18:33], v[42:45], v[62:65], v[18:33]
	ds_read_b128 v[58:61], v74 offset:61440
	ds_read_b128 v[54:57], v75 offset:61440
	ds_read_b128 v[50:53], v76 offset:61440
	ds_read_b128 v[62:65], v77 offset:61440
	s_nop 8
	v_max_f32_e32 v18, 0, v18
	v_max_f32_e32 v19, 0, v19
	v_fma_f32 v18, v174, v18, 0
	v_max_f32_e32 v20, 0, v20
	v_fmac_f32_e32 v18, v173, v19
	v_max_f32_e32 v21, 0, v21
	v_fmac_f32_e32 v18, v172, v20
	v_max_f32_e32 v22, 0, v22
	v_fmac_f32_e32 v18, v171, v21
	v_max_f32_e32 v23, 0, v23
	v_fmac_f32_e32 v18, v170, v22
	v_max_f32_e32 v24, 0, v24
	v_fmac_f32_e32 v18, v169, v23
	v_max_f32_e32 v25, 0, v25
	v_fmac_f32_e32 v18, v168, v24
	v_max_f32_e32 v26, 0, v26
	v_fmac_f32_e32 v18, v167, v25
	v_max_f32_e32 v27, 0, v27
	v_fmac_f32_e32 v18, v166, v26
	v_max_f32_e32 v28, 0, v28
	v_fmac_f32_e32 v18, v165, v27
	v_max_f32_e32 v29, 0, v29
	v_fmac_f32_e32 v18, v164, v28
	v_max_f32_e32 v30, 0, v30
	v_fmac_f32_e32 v18, v163, v29
	v_fmac_f32_e32 v18, v162, v30
	v_max_f32_e32 v19, 0, v31
	v_fmac_f32_e32 v18, v161, v19
	v_max_f32_e32 v19, 0, v32
	v_fmac_f32_e32 v18, v160, v19
	v_max_f32_e32 v19, 0, v33
	v_fmac_f32_e32 v18, v89, v19
	v_not_b32_e32 v19, v18
	v_or_b32_e32 v20, 0x80000000, v18
	v_cmp_gt_i32_e32 vcc, 0, v18
	s_nop 1
	v_cndmask_b32_e32 v18, v20, v19, vcc
	v_cmp_le_u32_e32 vcc, v111, v87
	s_nop 1
	v_cndmask_b32_e32 v192, 0, v18, vcc
.LBB0_465:
	s_or_b64 exec, exec, s[82:83]
	s_movk_i32 s2, 0x21f
	v_cmp_lt_u32_e32 vcc, s2, v177
	v_mov_b32_e32 v193, 0
	s_and_saveexec_b64 s[82:83], vcc
	s_cbranch_execz .LBB0_469
	s_movk_i32 s2, 0x23f
	s_waitcnt lgkmcnt(0)
	s_waitcnt vmcnt(0)
	s_barrier
	v_cmp_le_u32_e32 vcc, v79, v80
	s_and_b64 vcc, exec, vcc
	s_cbranch_vccz .Lidxd_s2
	s_nop 0
	global_load_lds_dwordx4 v72, s[100:101]
	s_add_u32 m0, m0, 0x400
	s_add_u32 s100, s100, 0x1a000
	s_addc_u32 s101, s101, 0
	s_nop 0
	global_load_lds_dwordx4 v73, s[100:101]
	s_add_u32 m0, m0, 0x400
	s_add_u32 s100, s100, 0x1a000
	s_addc_u32 s101, s101, 0
	s_nop 0
	global_load_lds_dwordx4 v72, s[100:101]
	s_add_u32 m0, m0, 0x400
	s_add_u32 s100, s100, 0x1a000
	s_addc_u32 s101, s101, 0
	s_nop 0
	global_load_lds_dwordx4 v73, s[100:101]
	s_add_u32 m0, m0, 0x400
	s_add_u32 s100, s100, 0x1a000
	s_addc_u32 s101, s101, 0
	s_sub_u32 m0, m0, 0x9000
	s_add_u32 s100, s100, 0x2d8000
	s_addc_u32 s101, s101, 0
	v_add_u32_e32 v79, 8, v79

.LBB0_468:
	s_or_b64 exec, exec, s[84:85]
	v_mfma_f32_32x32x16_bf16 v[18:33], v[38:41], v[58:61], 0
	v_mfma_f32_32x32x16_bf16 v[18:33], v[46:49], v[54:57], v[18:33]
	v_mfma_f32_32x32x16_bf16 v[18:33], v[34:37], v[50:53], v[18:33]
	v_mfma_f32_32x32x16_bf16 v[18:33], v[42:45], v[62:65], v[18:33]
	ds_read_b128 v[58:61], v74 offset:0
	ds_read_b128 v[54:57], v75 offset:0
	ds_read_b128 v[50:53], v76 offset:0
	ds_read_b128 v[62:65], v77 offset:0
	s_nop 8
	v_max_f32_e32 v18, 0, v18
	v_max_f32_e32 v19, 0, v19
	v_fma_f32 v18, v174, v18, 0
	v_max_f32_e32 v20, 0, v20
	v_fmac_f32_e32 v18, v173, v19
	v_max_f32_e32 v21, 0, v21
	v_fmac_f32_e32 v18, v172, v20
	v_max_f32_e32 v22, 0, v22
	v_fmac_f32_e32 v18, v171, v21
	v_max_f32_e32 v23, 0, v23
	v_fmac_f32_e32 v18, v170, v22
	v_max_f32_e32 v24, 0, v24
	v_fmac_f32_e32 v18, v169, v23
	v_max_f32_e32 v25, 0, v25
	v_fmac_f32_e32 v18, v168, v24
	v_max_f32_e32 v26, 0, v26
	v_fmac_f32_e32 v18, v167, v25
	v_max_f32_e32 v27, 0, v27
	v_fmac_f32_e32 v18, v166, v26
	v_max_f32_e32 v28, 0, v28
	v_fmac_f32_e32 v18, v165, v27
	v_max_f32_e32 v29, 0, v29
	v_fmac_f32_e32 v18, v164, v28
	v_max_f32_e32 v30, 0, v30
	v_fmac_f32_e32 v18, v163, v29
	v_fmac_f32_e32 v18, v162, v30
	v_max_f32_e32 v19, 0, v31
	v_fmac_f32_e32 v18, v161, v19
	v_max_f32_e32 v19, 0, v32
	v_fmac_f32_e32 v18, v160, v19
	v_max_f32_e32 v19, 0, v33
	v_fmac_f32_e32 v18, v89, v19
	v_not_b32_e32 v19, v18
	v_or_b32_e32 v20, 0x80000000, v18
	v_cmp_gt_i32_e32 vcc, 0, v18
	s_nop 1
	v_cndmask_b32_e32 v18, v20, v19, vcc
	v_cmp_le_u32_e32 vcc, v112, v87
	s_nop 1
	v_cndmask_b32_e32 v193, 0, v18, vcc

.LBB0_472:
	s_or_b64 exec, exec, s[84:85]
	v_mfma_f32_32x32x16_bf16 v[18:33], v[38:41], v[58:61], 0
	v_mfma_f32_32x32x16_bf16 v[18:33], v[46:49], v[54:57], v[18:33]
	v_mfma_f32_32x32x16_bf16 v[18:33], v[34:37], v[50:53], v[18:33]
	v_mfma_f32_32x32x16_bf16 v[18:33], v[42:45], v[62:65], v[18:33]
	ds_read_b128 v[58:61], v74 offset:4096
	ds_read_b128 v[54:57], v75 offset:4096
	ds_read_b128 v[50:53], v76 offset:4096
	ds_read_b128 v[62:65], v77 offset:4096
	s_nop 8
	v_max_f32_e32 v18, 0, v18
	v_max_f32_e32 v19, 0, v19
	v_fma_f32 v18, v174, v18, 0
	v_max_f32_e32 v20, 0, v20
	v_fmac_f32_e32 v18, v173, v19
	v_max_f32_e32 v21, 0, v21
	v_fmac_f32_e32 v18, v172, v20
	v_max_f32_e32 v22, 0, v22
	v_fmac_f32_e32 v18, v171, v21
	v_max_f32_e32 v23, 0, v23
	v_fmac_f32_e32 v18, v170, v22
	v_max_f32_e32 v24, 0, v24
	v_fmac_f32_e32 v18, v169, v23
	v_max_f32_e32 v25, 0, v25
	v_fmac_f32_e32 v18, v168, v24
	v_max_f32_e32 v26, 0, v26
	v_fmac_f32_e32 v18, v167, v25
	v_max_f32_e32 v27, 0, v27
	v_fmac_f32_e32 v18, v166, v26
	v_max_f32_e32 v28, 0, v28
	v_fmac_f32_e32 v18, v165, v27
	v_max_f32_e32 v29, 0, v29
	v_fmac_f32_e32 v18, v164, v28
	v_max_f32_e32 v30, 0, v30
	v_fmac_f32_e32 v18, v163, v29
	v_fmac_f32_e32 v18, v162, v30
	v_max_f32_e32 v19, 0, v31
	v_fmac_f32_e32 v18, v161, v19
	v_max_f32_e32 v19, 0, v32
	v_fmac_f32_e32 v18, v160, v19
	v_max_f32_e32 v19, 0, v33
	v_fmac_f32_e32 v18, v89, v19
	v_not_b32_e32 v19, v18
	v_or_b32_e32 v20, 0x80000000, v18
	v_cmp_gt_i32_e32 vcc, 0, v18
	s_nop 1
	v_cndmask_b32_e32 v18, v20, v19, vcc
	v_cmp_le_u32_e32 vcc, v113, v87
	s_nop 1
	v_cndmask_b32_e32 v194, 0, v18, vcc

.LBB0_476:
	s_or_b64 exec, exec, s[84:85]
	v_mfma_f32_32x32x16_bf16 v[18:33], v[38:41], v[58:61], 0
	v_mfma_f32_32x32x16_bf16 v[18:33], v[46:49], v[54:57], v[18:33]
	v_mfma_f32_32x32x16_bf16 v[18:33], v[34:37], v[50:53], v[18:33]
	v_mfma_f32_32x32x16_bf16 v[18:33], v[42:45], v[62:65], v[18:33]
	ds_read_b128 v[58:61], v74 offset:8192
	ds_read_b128 v[54:57], v75 offset:8192
	ds_read_b128 v[50:53], v76 offset:8192
	ds_read_b128 v[62:65], v77 offset:8192
	s_nop 8
	v_max_f32_e32 v18, 0, v18
	v_max_f32_e32 v19, 0, v19
	v_fma_f32 v18, v174, v18, 0
	v_max_f32_e32 v20, 0, v20
	v_fmac_f32_e32 v18, v173, v19
	v_max_f32_e32 v21, 0, v21
	v_fmac_f32_e32 v18, v172, v20
	v_max_f32_e32 v22, 0, v22
	v_fmac_f32_e32 v18, v171, v21
	v_max_f32_e32 v23, 0, v23
	v_fmac_f32_e32 v18, v170, v22
	v_max_f32_e32 v24, 0, v24
	v_fmac_f32_e32 v18, v169, v23
	v_max_f32_e32 v25, 0, v25
	v_fmac_f32_e32 v18, v168, v24
	v_max_f32_e32 v26, 0, v26
	v_fmac_f32_e32 v18, v167, v25
	v_max_f32_e32 v27, 0, v27
	v_fmac_f32_e32 v18, v166, v26
	v_max_f32_e32 v28, 0, v28
	v_fmac_f32_e32 v18, v165, v27
	v_max_f32_e32 v29, 0, v29
	v_fmac_f32_e32 v18, v164, v28
	v_max_f32_e32 v30, 0, v30
	v_fmac_f32_e32 v18, v163, v29
	v_fmac_f32_e32 v18, v162, v30
	v_max_f32_e32 v19, 0, v31
	v_fmac_f32_e32 v18, v161, v19
	v_max_f32_e32 v19, 0, v32
	v_fmac_f32_e32 v18, v160, v19
	v_max_f32_e32 v19, 0, v33
	v_fmac_f32_e32 v18, v89, v19
	v_not_b32_e32 v19, v18
	v_or_b32_e32 v20, 0x80000000, v18
	v_cmp_gt_i32_e32 vcc, 0, v18
	s_nop 1
	v_cndmask_b32_e32 v18, v20, v19, vcc
	v_cmp_le_u32_e32 vcc, v114, v87
	s_nop 1
	v_cndmask_b32_e32 v195, 0, v18, vcc

.LBB0_480:
	s_or_b64 exec, exec, s[84:85]
	v_mfma_f32_32x32x16_bf16 v[18:33], v[38:41], v[58:61], 0
	v_mfma_f32_32x32x16_bf16 v[18:33], v[46:49], v[54:57], v[18:33]
	v_mfma_f32_32x32x16_bf16 v[18:33], v[34:37], v[50:53], v[18:33]
	v_mfma_f32_32x32x16_bf16 v[18:33], v[42:45], v[62:65], v[18:33]
	ds_read_b128 v[58:61], v74 offset:12288
	ds_read_b128 v[54:57], v75 offset:12288
	ds_read_b128 v[50:53], v76 offset:12288
	ds_read_b128 v[62:65], v77 offset:12288
	s_nop 8
	v_max_f32_e32 v18, 0, v18
	v_max_f32_e32 v19, 0, v19
	v_fma_f32 v18, v174, v18, 0
	v_max_f32_e32 v20, 0, v20
	v_fmac_f32_e32 v18, v173, v19
	v_max_f32_e32 v21, 0, v21
	v_fmac_f32_e32 v18, v172, v20
	v_max_f32_e32 v22, 0, v22
	v_fmac_f32_e32 v18, v171, v21
	v_max_f32_e32 v23, 0, v23
	v_fmac_f32_e32 v18, v170, v22
	v_max_f32_e32 v24, 0, v24
	v_fmac_f32_e32 v18, v169, v23
	v_max_f32_e32 v25, 0, v25
	v_fmac_f32_e32 v18, v168, v24
	v_max_f32_e32 v26, 0, v26
	v_fmac_f32_e32 v18, v167, v25
	v_max_f32_e32 v27, 0, v27
	v_fmac_f32_e32 v18, v166, v26
	v_max_f32_e32 v28, 0, v28
	v_fmac_f32_e32 v18, v165, v27
	v_max_f32_e32 v29, 0, v29
	v_fmac_f32_e32 v18, v164, v28
	v_max_f32_e32 v30, 0, v30
	v_fmac_f32_e32 v18, v163, v29
	v_fmac_f32_e32 v18, v162, v30
	v_max_f32_e32 v19, 0, v31
	v_fmac_f32_e32 v18, v161, v19
	v_max_f32_e32 v19, 0, v32
	v_fmac_f32_e32 v18, v160, v19
	v_max_f32_e32 v19, 0, v33
	v_fmac_f32_e32 v18, v89, v19
	v_not_b32_e32 v19, v18
	v_or_b32_e32 v20, 0x80000000, v18
	v_cmp_gt_i32_e32 vcc, 0, v18
	s_nop 1
	v_cndmask_b32_e32 v18, v20, v19, vcc
	v_cmp_le_u32_e32 vcc, v115, v87
	s_nop 1
	v_cndmask_b32_e32 v196, 0, v18, vcc

.LBB0_484:
	s_or_b64 exec, exec, s[84:85]
	v_mfma_f32_32x32x16_bf16 v[18:33], v[38:41], v[58:61], 0
	v_mfma_f32_32x32x16_bf16 v[18:33], v[46:49], v[54:57], v[18:33]
	v_mfma_f32_32x32x16_bf16 v[18:33], v[34:37], v[50:53], v[18:33]
	v_mfma_f32_32x32x16_bf16 v[18:33], v[42:45], v[62:65], v[18:33]
	ds_read_b128 v[58:61], v74 offset:16384
	ds_read_b128 v[54:57], v75 offset:16384
	ds_read_b128 v[50:53], v76 offset:16384
	ds_read_b128 v[62:65], v77 offset:16384
	s_nop 8
	v_max_f32_e32 v18, 0, v18
	v_max_f32_e32 v19, 0, v19
	v_fma_f32 v18, v174, v18, 0
	v_max_f32_e32 v20, 0, v20
	v_fmac_f32_e32 v18, v173, v19
	v_max_f32_e32 v21, 0, v21
	v_fmac_f32_e32 v18, v172, v20
	v_max_f32_e32 v22, 0, v22
	v_fmac_f32_e32 v18, v171, v21
	v_max_f32_e32 v23, 0, v23
	v_fmac_f32_e32 v18, v170, v22
	v_max_f32_e32 v24, 0, v24
	v_fmac_f32_e32 v18, v169, v23
	v_max_f32_e32 v25, 0, v25
	v_fmac_f32_e32 v18, v168, v24
	v_max_f32_e32 v26, 0, v26
	v_fmac_f32_e32 v18, v167, v25
	v_max_f32_e32 v27, 0, v27
	v_fmac_f32_e32 v18, v166, v26
	v_max_f32_e32 v28, 0, v28
	v_fmac_f32_e32 v18, v165, v27
	v_max_f32_e32 v29, 0, v29
	v_fmac_f32_e32 v18, v164, v28
	v_max_f32_e32 v30, 0, v30
	v_fmac_f32_e32 v18, v163, v29
	v_fmac_f32_e32 v18, v162, v30
	v_max_f32_e32 v19, 0, v31
	v_fmac_f32_e32 v18, v161, v19
	v_max_f32_e32 v19, 0, v32
	v_fmac_f32_e32 v18, v160, v19
	v_max_f32_e32 v19, 0, v33
	v_fmac_f32_e32 v18, v89, v19
	v_not_b32_e32 v19, v18
	v_or_b32_e32 v20, 0x80000000, v18
	v_cmp_gt_i32_e32 vcc, 0, v18
	s_nop 1
	v_cndmask_b32_e32 v18, v20, v19, vcc
	v_cmp_le_u32_e32 vcc, v116, v87
	s_nop 1
	v_cndmask_b32_e32 v197, 0, v18, vcc

.LBB0_488:
	s_or_b64 exec, exec, s[84:85]
	v_mfma_f32_32x32x16_bf16 v[18:33], v[38:41], v[58:61], 0
	v_mfma_f32_32x32x16_bf16 v[18:33], v[46:49], v[54:57], v[18:33]
	v_mfma_f32_32x32x16_bf16 v[18:33], v[34:37], v[50:53], v[18:33]
	v_mfma_f32_32x32x16_bf16 v[18:33], v[42:45], v[62:65], v[18:33]
	ds_read_b128 v[58:61], v74 offset:20480
	ds_read_b128 v[54:57], v75 offset:20480
	ds_read_b128 v[50:53], v76 offset:20480
	ds_read_b128 v[62:65], v77 offset:20480
	s_nop 8
	v_max_f32_e32 v18, 0, v18
	v_max_f32_e32 v19, 0, v19
	v_fma_f32 v18, v174, v18, 0
	v_max_f32_e32 v20, 0, v20
	v_fmac_f32_e32 v18, v173, v19
	v_max_f32_e32 v21, 0, v21
	v_fmac_f32_e32 v18, v172, v20
	v_max_f32_e32 v22, 0, v22
	v_fmac_f32_e32 v18, v171, v21
	v_max_f32_e32 v23, 0, v23
	v_fmac_f32_e32 v18, v170, v22
	v_max_f32_e32 v24, 0, v24
	v_fmac_f32_e32 v18, v169, v23
	v_max_f32_e32 v25, 0, v25
	v_fmac_f32_e32 v18, v168, v24
	v_max_f32_e32 v26, 0, v26
	v_fmac_f32_e32 v18, v167, v25
	v_max_f32_e32 v27, 0, v27
	v_fmac_f32_e32 v18, v166, v26
	v_max_f32_e32 v28, 0, v28
	v_fmac_f32_e32 v18, v165, v27
	v_max_f32_e32 v29, 0, v29
	v_fmac_f32_e32 v18, v164, v28
	v_max_f32_e32 v30, 0, v30
	v_fmac_f32_e32 v18, v163, v29
	v_fmac_f32_e32 v18, v162, v30
	v_max_f32_e32 v19, 0, v31
	v_fmac_f32_e32 v18, v161, v19
	v_max_f32_e32 v19, 0, v32
	v_fmac_f32_e32 v18, v160, v19
	v_max_f32_e32 v19, 0, v33
	v_fmac_f32_e32 v18, v89, v19
	v_not_b32_e32 v19, v18
	v_or_b32_e32 v20, 0x80000000, v18
	v_cmp_gt_i32_e32 vcc, 0, v18
	s_nop 1
	v_cndmask_b32_e32 v18, v20, v19, vcc
	v_cmp_le_u32_e32 vcc, v117, v87
	s_nop 1
	v_cndmask_b32_e32 v216, 0, v18, vcc

.LBB0_492:
	s_or_b64 exec, exec, s[84:85]
	v_mfma_f32_32x32x16_bf16 v[18:33], v[38:41], v[58:61], 0
	v_mfma_f32_32x32x16_bf16 v[18:33], v[46:49], v[54:57], v[18:33]
	v_mfma_f32_32x32x16_bf16 v[18:33], v[34:37], v[50:53], v[18:33]
	v_mfma_f32_32x32x16_bf16 v[18:33], v[42:45], v[62:65], v[18:33]
	ds_read_b128 v[58:61], v74 offset:24576
	ds_read_b128 v[54:57], v75 offset:24576
	ds_read_b128 v[50:53], v76 offset:24576
	ds_read_b128 v[62:65], v77 offset:24576
	s_nop 8
	v_max_f32_e32 v18, 0, v18
	v_max_f32_e32 v19, 0, v19
	v_fma_f32 v18, v174, v18, 0
	v_max_f32_e32 v20, 0, v20
	v_fmac_f32_e32 v18, v173, v19
	v_max_f32_e32 v21, 0, v21
	v_fmac_f32_e32 v18, v172, v20
	v_max_f32_e32 v22, 0, v22
	v_fmac_f32_e32 v18, v171, v21
	v_max_f32_e32 v23, 0, v23
	v_fmac_f32_e32 v18, v170, v22
	v_max_f32_e32 v24, 0, v24
	v_fmac_f32_e32 v18, v169, v23
	v_max_f32_e32 v25, 0, v25
	v_fmac_f32_e32 v18, v168, v24
	v_max_f32_e32 v26, 0, v26
	v_fmac_f32_e32 v18, v167, v25
	v_max_f32_e32 v27, 0, v27
	v_fmac_f32_e32 v18, v166, v26
	v_max_f32_e32 v28, 0, v28
	v_fmac_f32_e32 v18, v165, v27
	v_max_f32_e32 v29, 0, v29
	v_fmac_f32_e32 v18, v164, v28
	v_max_f32_e32 v30, 0, v30
	v_fmac_f32_e32 v18, v163, v29
	v_fmac_f32_e32 v18, v162, v30
	v_max_f32_e32 v19, 0, v31
	v_fmac_f32_e32 v18, v161, v19
	v_max_f32_e32 v19, 0, v32
	v_fmac_f32_e32 v18, v160, v19
	v_max_f32_e32 v19, 0, v33
	v_fmac_f32_e32 v18, v89, v19
	v_not_b32_e32 v19, v18
	v_or_b32_e32 v20, 0x80000000, v18
	v_cmp_gt_i32_e32 vcc, 0, v18
	s_nop 1
	v_cndmask_b32_e32 v18, v20, v19, vcc
	v_cmp_le_u32_e32 vcc, v118, v87
	s_nop 1
	v_cndmask_b32_e32 v217, 0, v18, vcc

.LBB0_496:
	s_or_b64 exec, exec, s[84:85]
	v_mfma_f32_32x32x16_bf16 v[18:33], v[38:41], v[58:61], 0
	v_mfma_f32_32x32x16_bf16 v[18:33], v[46:49], v[54:57], v[18:33]
	v_mfma_f32_32x32x16_bf16 v[18:33], v[34:37], v[50:53], v[18:33]
	v_mfma_f32_32x32x16_bf16 v[18:33], v[42:45], v[62:65], v[18:33]
	ds_read_b128 v[58:61], v74 offset:28672
	ds_read_b128 v[54:57], v75 offset:28672
	ds_read_b128 v[50:53], v76 offset:28672
	ds_read_b128 v[62:65], v77 offset:28672
	s_nop 8
	v_max_f32_e32 v18, 0, v18
	v_max_f32_e32 v19, 0, v19
	v_fma_f32 v18, v174, v18, 0
	v_max_f32_e32 v20, 0, v20
	v_fmac_f32_e32 v18, v173, v19
	v_max_f32_e32 v21, 0, v21
	v_fmac_f32_e32 v18, v172, v20
	v_max_f32_e32 v22, 0, v22
	v_fmac_f32_e32 v18, v171, v21
	v_max_f32_e32 v23, 0, v23
	v_fmac_f32_e32 v18, v170, v22
	v_max_f32_e32 v24, 0, v24
	v_fmac_f32_e32 v18, v169, v23
	v_max_f32_e32 v25, 0, v25
	v_fmac_f32_e32 v18, v168, v24
	v_max_f32_e32 v26, 0, v26
	v_fmac_f32_e32 v18, v167, v25
	v_max_f32_e32 v27, 0, v27
	v_fmac_f32_e32 v18, v166, v26
	v_max_f32_e32 v28, 0, v28
	v_fmac_f32_e32 v18, v165, v27
	v_max_f32_e32 v29, 0, v29
	v_fmac_f32_e32 v18, v164, v28
	v_max_f32_e32 v30, 0, v30
	v_fmac_f32_e32 v18, v163, v29
	v_fmac_f32_e32 v18, v162, v30
	v_max_f32_e32 v19, 0, v31
	v_fmac_f32_e32 v18, v161, v19
	v_max_f32_e32 v19, 0, v32
	v_fmac_f32_e32 v18, v160, v19
	v_max_f32_e32 v19, 0, v33
	v_fmac_f32_e32 v18, v89, v19
	v_not_b32_e32 v19, v18
	v_or_b32_e32 v20, 0x80000000, v18
	v_cmp_gt_i32_e32 vcc, 0, v18
	s_nop 1
	v_cndmask_b32_e32 v18, v20, v19, vcc
	v_cmp_le_u32_e32 vcc, v119, v87
	s_nop 1
	v_cndmask_b32_e32 v218, 0, v18, vcc
.LBB0_497:
	s_or_b64 exec, exec, s[82:83]
	s_movk_i32 s2, 0x31f
	v_cmp_lt_u32_e32 vcc, s2, v177
	v_mov_b32_e32 v219, 0
	s_and_saveexec_b64 s[82:83], vcc
	s_cbranch_execz .LBB0_501
	s_movk_i32 s2, 0x33f
	s_waitcnt lgkmcnt(0)
	s_waitcnt vmcnt(0)
	s_barrier
	v_cmp_le_u32_e32 vcc, v79, v80
	s_and_b64 vcc, exec, vcc
	s_cbranch_vccz .Lidxd_s3
	s_nop 0
	global_load_lds_dwordx4 v72, s[100:101]
	s_add_u32 m0, m0, 0x400
	s_add_u32 s100, s100, 0x1a000
	s_addc_u32 s101, s101, 0
	s_nop 0
	global_load_lds_dwordx4 v73, s[100:101]
	s_add_u32 m0, m0, 0x400
	s_add_u32 s100, s100, 0x1a000
	s_addc_u32 s101, s101, 0
	s_nop 0
	global_load_lds_dwordx4 v72, s[100:101]
	s_add_u32 m0, m0, 0x400
	s_add_u32 s100, s100, 0x1a000
	s_addc_u32 s101, s101, 0
	s_nop 0
	global_load_lds_dwordx4 v73, s[100:101]
	s_add_u32 m0, m0, 0x400
	s_add_u32 s100, s100, 0x1a000
	s_addc_u32 s101, s101, 0
	s_add_u32 m0, m0, 0x7000
	s_add_u32 s100, s100, 0x2d8000
	s_addc_u32 s101, s101, 0
	v_add_u32_e32 v79, 8, v79

.LBB0_500:
	s_or_b64 exec, exec, s[84:85]
	v_mfma_f32_32x32x16_bf16 v[18:33], v[38:41], v[58:61], 0
	v_mfma_f32_32x32x16_bf16 v[18:33], v[46:49], v[54:57], v[18:33]
	v_mfma_f32_32x32x16_bf16 v[18:33], v[34:37], v[50:53], v[18:33]
	v_mfma_f32_32x32x16_bf16 v[18:33], v[42:45], v[62:65], v[18:33]
	ds_read_b128 v[58:61], v74 offset:32768
	ds_read_b128 v[54:57], v75 offset:32768
	ds_read_b128 v[50:53], v76 offset:32768
	ds_read_b128 v[62:65], v77 offset:32768
	s_nop 8
	v_max_f32_e32 v18, 0, v18
	v_max_f32_e32 v19, 0, v19
	v_fma_f32 v18, v174, v18, 0
	v_max_f32_e32 v20, 0, v20
	v_fmac_f32_e32 v18, v173, v19
	v_max_f32_e32 v21, 0, v21
	v_fmac_f32_e32 v18, v172, v20
	v_max_f32_e32 v22, 0, v22
	v_fmac_f32_e32 v18, v171, v21
	v_max_f32_e32 v23, 0, v23
	v_fmac_f32_e32 v18, v170, v22
	v_max_f32_e32 v24, 0, v24
	v_fmac_f32_e32 v18, v169, v23
	v_max_f32_e32 v25, 0, v25
	v_fmac_f32_e32 v18, v168, v24
	v_max_f32_e32 v26, 0, v26
	v_fmac_f32_e32 v18, v167, v25
	v_max_f32_e32 v27, 0, v27
	v_fmac_f32_e32 v18, v166, v26
	v_max_f32_e32 v28, 0, v28
	v_fmac_f32_e32 v18, v165, v27
	v_max_f32_e32 v29, 0, v29
	v_fmac_f32_e32 v18, v164, v28
	v_max_f32_e32 v30, 0, v30
	v_fmac_f32_e32 v18, v163, v29
	v_fmac_f32_e32 v18, v162, v30
	v_max_f32_e32 v19, 0, v31
	v_fmac_f32_e32 v18, v161, v19
	v_max_f32_e32 v19, 0, v32
	v_fmac_f32_e32 v18, v160, v19
	v_max_f32_e32 v19, 0, v33
	v_fmac_f32_e32 v18, v89, v19
	v_not_b32_e32 v19, v18
	v_or_b32_e32 v20, 0x80000000, v18
	v_cmp_gt_i32_e32 vcc, 0, v18
	s_nop 1
	v_cndmask_b32_e32 v18, v20, v19, vcc
	v_cmp_le_u32_e32 vcc, v120, v87
	s_nop 1
	v_cndmask_b32_e32 v219, 0, v18, vcc

.LBB0_504:
	s_or_b64 exec, exec, s[84:85]
	v_mfma_f32_32x32x16_bf16 v[18:33], v[38:41], v[58:61], 0
	v_mfma_f32_32x32x16_bf16 v[18:33], v[46:49], v[54:57], v[18:33]
	v_mfma_f32_32x32x16_bf16 v[18:33], v[34:37], v[50:53], v[18:33]
	v_mfma_f32_32x32x16_bf16 v[18:33], v[42:45], v[62:65], v[18:33]
	ds_read_b128 v[58:61], v74 offset:36864
	ds_read_b128 v[54:57], v75 offset:36864
	ds_read_b128 v[50:53], v76 offset:36864
	ds_read_b128 v[62:65], v77 offset:36864
	s_nop 8
	v_max_f32_e32 v18, 0, v18
	v_max_f32_e32 v19, 0, v19
	v_fma_f32 v18, v174, v18, 0
	v_max_f32_e32 v20, 0, v20
	v_fmac_f32_e32 v18, v173, v19
	v_max_f32_e32 v21, 0, v21
	v_fmac_f32_e32 v18, v172, v20
	v_max_f32_e32 v22, 0, v22
	v_fmac_f32_e32 v18, v171, v21
	v_max_f32_e32 v23, 0, v23
	v_fmac_f32_e32 v18, v170, v22
	v_max_f32_e32 v24, 0, v24
	v_fmac_f32_e32 v18, v169, v23
	v_max_f32_e32 v25, 0, v25
	v_fmac_f32_e32 v18, v168, v24
	v_max_f32_e32 v26, 0, v26
	v_fmac_f32_e32 v18, v167, v25
	v_max_f32_e32 v27, 0, v27
	v_fmac_f32_e32 v18, v166, v26
	v_max_f32_e32 v28, 0, v28
	v_fmac_f32_e32 v18, v165, v27
	v_max_f32_e32 v29, 0, v29
	v_fmac_f32_e32 v18, v164, v28
	v_max_f32_e32 v30, 0, v30
	v_fmac_f32_e32 v18, v163, v29
	v_fmac_f32_e32 v18, v162, v30
	v_max_f32_e32 v19, 0, v31
	v_fmac_f32_e32 v18, v161, v19
	v_max_f32_e32 v19, 0, v32
	v_fmac_f32_e32 v18, v160, v19
	v_max_f32_e32 v19, 0, v33
	v_fmac_f32_e32 v18, v89, v19
	v_not_b32_e32 v19, v18
	v_or_b32_e32 v20, 0x80000000, v18
	v_cmp_gt_i32_e32 vcc, 0, v18
	s_nop 1
	v_cndmask_b32_e32 v18, v20, v19, vcc
	v_cmp_le_u32_e32 vcc, v121, v87
	s_nop 1
	v_cndmask_b32_e32 v220, 0, v18, vcc

.LBB0_508:
	s_or_b64 exec, exec, s[84:85]
	v_mfma_f32_32x32x16_bf16 v[18:33], v[38:41], v[58:61], 0
	v_mfma_f32_32x32x16_bf16 v[18:33], v[46:49], v[54:57], v[18:33]
	v_mfma_f32_32x32x16_bf16 v[18:33], v[34:37], v[50:53], v[18:33]
	v_mfma_f32_32x32x16_bf16 v[18:33], v[42:45], v[62:65], v[18:33]
	ds_read_b128 v[58:61], v74 offset:40960
	ds_read_b128 v[54:57], v75 offset:40960
	ds_read_b128 v[50:53], v76 offset:40960
	ds_read_b128 v[62:65], v77 offset:40960
	s_nop 8
	v_max_f32_e32 v18, 0, v18
	v_max_f32_e32 v19, 0, v19
	v_fma_f32 v18, v174, v18, 0
	v_max_f32_e32 v20, 0, v20
	v_fmac_f32_e32 v18, v173, v19
	v_max_f32_e32 v21, 0, v21
	v_fmac_f32_e32 v18, v172, v20
	v_max_f32_e32 v22, 0, v22
	v_fmac_f32_e32 v18, v171, v21
	v_max_f32_e32 v23, 0, v23
	v_fmac_f32_e32 v18, v170, v22
	v_max_f32_e32 v24, 0, v24
	v_fmac_f32_e32 v18, v169, v23
	v_max_f32_e32 v25, 0, v25
	v_fmac_f32_e32 v18, v168, v24
	v_max_f32_e32 v26, 0, v26
	v_fmac_f32_e32 v18, v167, v25
	v_max_f32_e32 v27, 0, v27
	v_fmac_f32_e32 v18, v166, v26
	v_max_f32_e32 v28, 0, v28
	v_fmac_f32_e32 v18, v165, v27
	v_max_f32_e32 v29, 0, v29
	v_fmac_f32_e32 v18, v164, v28
	v_max_f32_e32 v30, 0, v30
	v_fmac_f32_e32 v18, v163, v29
	v_fmac_f32_e32 v18, v162, v30
	v_max_f32_e32 v19, 0, v31
	v_fmac_f32_e32 v18, v161, v19
	v_max_f32_e32 v19, 0, v32
	v_fmac_f32_e32 v18, v160, v19
	v_max_f32_e32 v19, 0, v33
	v_fmac_f32_e32 v18, v89, v19
	v_not_b32_e32 v19, v18
	v_or_b32_e32 v20, 0x80000000, v18
	v_cmp_gt_i32_e32 vcc, 0, v18
	s_nop 1
	v_cndmask_b32_e32 v18, v20, v19, vcc
	v_cmp_le_u32_e32 vcc, v122, v87
	s_nop 1
	v_cndmask_b32_e32 v221, 0, v18, vcc

.LBB0_512:
	s_or_b64 exec, exec, s[84:85]
	v_mfma_f32_32x32x16_bf16 v[18:33], v[38:41], v[58:61], 0
	v_mfma_f32_32x32x16_bf16 v[18:33], v[46:49], v[54:57], v[18:33]
	v_mfma_f32_32x32x16_bf16 v[18:33], v[34:37], v[50:53], v[18:33]
	v_mfma_f32_32x32x16_bf16 v[18:33], v[42:45], v[62:65], v[18:33]
	ds_read_b128 v[58:61], v74 offset:45056
	ds_read_b128 v[54:57], v75 offset:45056
	ds_read_b128 v[50:53], v76 offset:45056
	ds_read_b128 v[62:65], v77 offset:45056
	s_nop 8
	v_max_f32_e32 v18, 0, v18
	v_max_f32_e32 v19, 0, v19
	v_fma_f32 v18, v174, v18, 0
	v_max_f32_e32 v20, 0, v20
	v_fmac_f32_e32 v18, v173, v19
	v_max_f32_e32 v21, 0, v21
	v_fmac_f32_e32 v18, v172, v20
	v_max_f32_e32 v22, 0, v22
	v_fmac_f32_e32 v18, v171, v21
	v_max_f32_e32 v23, 0, v23
	v_fmac_f32_e32 v18, v170, v22
	v_max_f32_e32 v24, 0, v24
	v_fmac_f32_e32 v18, v169, v23
	v_max_f32_e32 v25, 0, v25
	v_fmac_f32_e32 v18, v168, v24
	v_max_f32_e32 v26, 0, v26
	v_fmac_f32_e32 v18, v167, v25
	v_max_f32_e32 v27, 0, v27
	v_fmac_f32_e32 v18, v166, v26
	v_max_f32_e32 v28, 0, v28
	v_fmac_f32_e32 v18, v165, v27
	v_max_f32_e32 v29, 0, v29
	v_fmac_f32_e32 v18, v164, v28
	v_max_f32_e32 v30, 0, v30
	v_fmac_f32_e32 v18, v163, v29
	v_fmac_f32_e32 v18, v162, v30
	v_max_f32_e32 v19, 0, v31
	v_fmac_f32_e32 v18, v161, v19
	v_max_f32_e32 v19, 0, v32
	v_fmac_f32_e32 v18, v160, v19
	v_max_f32_e32 v19, 0, v33
	v_fmac_f32_e32 v18, v89, v19
	v_not_b32_e32 v19, v18
	v_or_b32_e32 v20, 0x80000000, v18
	v_cmp_gt_i32_e32 vcc, 0, v18
	s_nop 1
	v_cndmask_b32_e32 v18, v20, v19, vcc
	v_cmp_le_u32_e32 vcc, v123, v87
	s_nop 1
	v_cndmask_b32_e32 v222, 0, v18, vcc

.LBB0_516:
	s_or_b64 exec, exec, s[84:85]
	v_mfma_f32_32x32x16_bf16 v[18:33], v[38:41], v[58:61], 0
	v_mfma_f32_32x32x16_bf16 v[18:33], v[46:49], v[54:57], v[18:33]
	v_mfma_f32_32x32x16_bf16 v[18:33], v[34:37], v[50:53], v[18:33]
	v_mfma_f32_32x32x16_bf16 v[18:33], v[42:45], v[62:65], v[18:33]
	ds_read_b128 v[58:61], v74 offset:49152
	ds_read_b128 v[54:57], v75 offset:49152
	ds_read_b128 v[50:53], v76 offset:49152
	ds_read_b128 v[62:65], v77 offset:49152
	s_nop 8
	v_max_f32_e32 v18, 0, v18
	v_max_f32_e32 v19, 0, v19
	v_fma_f32 v18, v174, v18, 0
	v_max_f32_e32 v20, 0, v20
	v_fmac_f32_e32 v18, v173, v19
	v_max_f32_e32 v21, 0, v21
	v_fmac_f32_e32 v18, v172, v20
	v_max_f32_e32 v22, 0, v22
	v_fmac_f32_e32 v18, v171, v21
	v_max_f32_e32 v23, 0, v23
	v_fmac_f32_e32 v18, v170, v22
	v_max_f32_e32 v24, 0, v24
	v_fmac_f32_e32 v18, v169, v23
	v_max_f32_e32 v25, 0, v25
	v_fmac_f32_e32 v18, v168, v24
	v_max_f32_e32 v26, 0, v26
	v_fmac_f32_e32 v18, v167, v25
	v_max_f32_e32 v27, 0, v27
	v_fmac_f32_e32 v18, v166, v26
	v_max_f32_e32 v28, 0, v28
	v_fmac_f32_e32 v18, v165, v27
	v_max_f32_e32 v29, 0, v29
	v_fmac_f32_e32 v18, v164, v28
	v_max_f32_e32 v30, 0, v30
	v_fmac_f32_e32 v18, v163, v29
	v_fmac_f32_e32 v18, v162, v30
	v_max_f32_e32 v19, 0, v31
	v_fmac_f32_e32 v18, v161, v19
	v_max_f32_e32 v19, 0, v32
	v_fmac_f32_e32 v18, v160, v19
	v_max_f32_e32 v19, 0, v33
	v_fmac_f32_e32 v18, v89, v19
	v_not_b32_e32 v19, v18
	v_or_b32_e32 v20, 0x80000000, v18
	v_cmp_gt_i32_e32 vcc, 0, v18
	s_nop 1
	v_cndmask_b32_e32 v18, v20, v19, vcc
	v_cmp_le_u32_e32 vcc, v124, v87
	s_nop 1
	v_cndmask_b32_e32 v223, 0, v18, vcc

.LBB0_520:
	s_or_b64 exec, exec, s[84:85]
	v_mfma_f32_32x32x16_bf16 v[18:33], v[38:41], v[58:61], 0
	v_mfma_f32_32x32x16_bf16 v[18:33], v[46:49], v[54:57], v[18:33]
	v_mfma_f32_32x32x16_bf16 v[18:33], v[34:37], v[50:53], v[18:33]
	v_mfma_f32_32x32x16_bf16 v[18:33], v[42:45], v[62:65], v[18:33]
	ds_read_b128 v[58:61], v74 offset:53248
	ds_read_b128 v[54:57], v75 offset:53248
	ds_read_b128 v[50:53], v76 offset:53248
	ds_read_b128 v[62:65], v77 offset:53248
	s_nop 8
	v_max_f32_e32 v18, 0, v18
	v_max_f32_e32 v19, 0, v19
	v_fma_f32 v18, v174, v18, 0
	v_max_f32_e32 v20, 0, v20
	v_fmac_f32_e32 v18, v173, v19
	v_max_f32_e32 v21, 0, v21
	v_fmac_f32_e32 v18, v172, v20
	v_max_f32_e32 v22, 0, v22
	v_fmac_f32_e32 v18, v171, v21
	v_max_f32_e32 v23, 0, v23
	v_fmac_f32_e32 v18, v170, v22
	v_max_f32_e32 v24, 0, v24
	v_fmac_f32_e32 v18, v169, v23
	v_max_f32_e32 v25, 0, v25
	v_fmac_f32_e32 v18, v168, v24
	v_max_f32_e32 v26, 0, v26
	v_fmac_f32_e32 v18, v167, v25
	v_max_f32_e32 v27, 0, v27
	v_fmac_f32_e32 v18, v166, v26
	v_max_f32_e32 v28, 0, v28
	v_fmac_f32_e32 v18, v165, v27
	v_max_f32_e32 v29, 0, v29
	v_fmac_f32_e32 v18, v164, v28
	v_max_f32_e32 v30, 0, v30
	v_fmac_f32_e32 v18, v163, v29
	v_fmac_f32_e32 v18, v162, v30
	v_max_f32_e32 v19, 0, v31
	v_fmac_f32_e32 v18, v161, v19
	v_max_f32_e32 v19, 0, v32
	v_fmac_f32_e32 v18, v160, v19
	v_max_f32_e32 v19, 0, v33
	v_fmac_f32_e32 v18, v89, v19
	v_not_b32_e32 v19, v18
	v_or_b32_e32 v20, 0x80000000, v18
	v_cmp_gt_i32_e32 vcc, 0, v18
	s_nop 1
	v_cndmask_b32_e32 v18, v20, v19, vcc
	v_cmp_le_u32_e32 vcc, v125, v87
	s_nop 1
	v_cndmask_b32_e32 v224, 0, v18, vcc

.LBB0_524:
	s_or_b64 exec, exec, s[84:85]
	v_mfma_f32_32x32x16_bf16 v[18:33], v[38:41], v[58:61], 0
	v_mfma_f32_32x32x16_bf16 v[18:33], v[46:49], v[54:57], v[18:33]
	v_mfma_f32_32x32x16_bf16 v[18:33], v[34:37], v[50:53], v[18:33]
	v_mfma_f32_32x32x16_bf16 v[18:33], v[42:45], v[62:65], v[18:33]
	ds_read_b128 v[58:61], v74 offset:57344
	ds_read_b128 v[54:57], v75 offset:57344
	ds_read_b128 v[50:53], v76 offset:57344
	ds_read_b128 v[62:65], v77 offset:57344
	s_nop 8
	v_max_f32_e32 v18, 0, v18
	v_max_f32_e32 v19, 0, v19
	v_fma_f32 v18, v174, v18, 0
	v_max_f32_e32 v20, 0, v20
	v_fmac_f32_e32 v18, v173, v19
	v_max_f32_e32 v21, 0, v21
	v_fmac_f32_e32 v18, v172, v20
	v_max_f32_e32 v22, 0, v22
	v_fmac_f32_e32 v18, v171, v21
	v_max_f32_e32 v23, 0, v23
	v_fmac_f32_e32 v18, v170, v22
	v_max_f32_e32 v24, 0, v24
	v_fmac_f32_e32 v18, v169, v23
	v_max_f32_e32 v25, 0, v25
	v_fmac_f32_e32 v18, v168, v24
	v_max_f32_e32 v26, 0, v26
	v_fmac_f32_e32 v18, v167, v25
	v_max_f32_e32 v27, 0, v27
	v_fmac_f32_e32 v18, v166, v26
	v_max_f32_e32 v28, 0, v28
	v_fmac_f32_e32 v18, v165, v27
	v_max_f32_e32 v29, 0, v29
	v_fmac_f32_e32 v18, v164, v28
	v_max_f32_e32 v30, 0, v30
	v_fmac_f32_e32 v18, v163, v29
	v_fmac_f32_e32 v18, v162, v30
	v_max_f32_e32 v19, 0, v31
	v_fmac_f32_e32 v18, v161, v19
	v_max_f32_e32 v19, 0, v32
	v_fmac_f32_e32 v18, v160, v19
	v_max_f32_e32 v19, 0, v33
	v_fmac_f32_e32 v18, v89, v19
	v_not_b32_e32 v19, v18
	v_or_b32_e32 v20, 0x80000000, v18
	v_cmp_gt_i32_e32 vcc, 0, v18
	s_nop 1
	v_cndmask_b32_e32 v18, v20, v19, vcc
	v_cmp_le_u32_e32 vcc, v126, v87
	s_nop 1
	v_cndmask_b32_e32 v225, 0, v18, vcc

.LBB0_528:
	s_or_b64 exec, exec, s[84:85]
	v_mfma_f32_32x32x16_bf16 v[18:33], v[38:41], v[58:61], 0
	v_mfma_f32_32x32x16_bf16 v[18:33], v[46:49], v[54:57], v[18:33]
	v_mfma_f32_32x32x16_bf16 v[18:33], v[34:37], v[50:53], v[18:33]
	v_mfma_f32_32x32x16_bf16 v[18:33], v[42:45], v[62:65], v[18:33]
	ds_read_b128 v[58:61], v74 offset:61440
	ds_read_b128 v[54:57], v75 offset:61440
	ds_read_b128 v[50:53], v76 offset:61440
	ds_read_b128 v[62:65], v77 offset:61440
	s_nop 8
	v_max_f32_e32 v18, 0, v18
	v_max_f32_e32 v19, 0, v19
	v_fma_f32 v18, v174, v18, 0
	v_max_f32_e32 v20, 0, v20
	v_fmac_f32_e32 v18, v173, v19
	v_max_f32_e32 v21, 0, v21
	v_fmac_f32_e32 v18, v172, v20
	v_max_f32_e32 v22, 0, v22
	v_fmac_f32_e32 v18, v171, v21
	v_max_f32_e32 v23, 0, v23
	v_fmac_f32_e32 v18, v170, v22
	v_max_f32_e32 v24, 0, v24
	v_fmac_f32_e32 v18, v169, v23
	v_max_f32_e32 v25, 0, v25
	v_fmac_f32_e32 v18, v168, v24
	v_max_f32_e32 v26, 0, v26
	v_fmac_f32_e32 v18, v167, v25
	v_max_f32_e32 v27, 0, v27
	v_fmac_f32_e32 v18, v166, v26
	v_max_f32_e32 v28, 0, v28
	v_fmac_f32_e32 v18, v165, v27
	v_max_f32_e32 v29, 0, v29
	v_fmac_f32_e32 v18, v164, v28
	v_max_f32_e32 v30, 0, v30
	v_fmac_f32_e32 v18, v163, v29
	v_fmac_f32_e32 v18, v162, v30
	v_max_f32_e32 v19, 0, v31
	v_fmac_f32_e32 v18, v161, v19
	v_max_f32_e32 v19, 0, v32
	v_fmac_f32_e32 v18, v160, v19
	v_max_f32_e32 v19, 0, v33
	v_fmac_f32_e32 v18, v89, v19
	v_not_b32_e32 v19, v18
	v_or_b32_e32 v20, 0x80000000, v18
	v_cmp_gt_i32_e32 vcc, 0, v18
	s_nop 1
	v_cndmask_b32_e32 v18, v20, v19, vcc
	v_cmp_le_u32_e32 vcc, v127, v87
	s_nop 1
	v_cndmask_b32_e32 v226, 0, v18, vcc
.LBB0_529:
	s_or_b64 exec, exec, s[82:83]
	s_movk_i32 s2, 0x41f
	v_cmp_lt_u32_e32 vcc, s2, v177
	v_mov_b32_e32 v227, 0
	s_and_saveexec_b64 s[82:83], vcc
	s_cbranch_execz .LBB0_533
	s_movk_i32 s2, 0x43f
	s_waitcnt lgkmcnt(0)
	s_waitcnt vmcnt(0)
	s_barrier
	v_cmp_le_u32_e32 vcc, v79, v80
	s_and_b64 vcc, exec, vcc
	s_cbranch_vccz .Lidxd_s4
	s_nop 0
	global_load_lds_dwordx4 v72, s[100:101]
	s_add_u32 m0, m0, 0x400
	s_add_u32 s100, s100, 0x1a000
	s_addc_u32 s101, s101, 0
	s_nop 0
	global_load_lds_dwordx4 v73, s[100:101]
	s_add_u32 m0, m0, 0x400
	s_add_u32 s100, s100, 0x1a000
	s_addc_u32 s101, s101, 0
	s_nop 0
	global_load_lds_dwordx4 v72, s[100:101]
	s_add_u32 m0, m0, 0x400
	s_add_u32 s100, s100, 0x1a000
	s_addc_u32 s101, s101, 0
	s_nop 0
	global_load_lds_dwordx4 v73, s[100:101]
	s_add_u32 m0, m0, 0x400
	s_add_u32 s100, s100, 0x1a000
	s_addc_u32 s101, s101, 0
	s_sub_u32 m0, m0, 0x9000
	s_add_u32 s100, s100, 0x2d8000
	s_addc_u32 s101, s101, 0
	v_add_u32_e32 v79, 8, v79

.LBB0_532:
	s_or_b64 exec, exec, s[84:85]
	v_mfma_f32_32x32x16_bf16 v[18:33], v[38:41], v[58:61], 0
	v_mfma_f32_32x32x16_bf16 v[18:33], v[46:49], v[54:57], v[18:33]
	v_mfma_f32_32x32x16_bf16 v[18:33], v[34:37], v[50:53], v[18:33]
	v_mfma_f32_32x32x16_bf16 v[18:33], v[42:45], v[62:65], v[18:33]
	ds_read_b128 v[58:61], v74 offset:0
	ds_read_b128 v[54:57], v75 offset:0
	ds_read_b128 v[50:53], v76 offset:0
	ds_read_b128 v[62:65], v77 offset:0
	s_nop 8
	v_max_f32_e32 v18, 0, v18
	v_max_f32_e32 v19, 0, v19
	v_fma_f32 v18, v174, v18, 0
	v_max_f32_e32 v20, 0, v20
	v_fmac_f32_e32 v18, v173, v19
	v_max_f32_e32 v21, 0, v21
	v_fmac_f32_e32 v18, v172, v20
	v_max_f32_e32 v22, 0, v22
	v_fmac_f32_e32 v18, v171, v21
	v_max_f32_e32 v23, 0, v23
	v_fmac_f32_e32 v18, v170, v22
	v_max_f32_e32 v24, 0, v24
	v_fmac_f32_e32 v18, v169, v23
	v_max_f32_e32 v25, 0, v25
	v_fmac_f32_e32 v18, v168, v24
	v_max_f32_e32 v26, 0, v26
	v_fmac_f32_e32 v18, v167, v25
	v_max_f32_e32 v27, 0, v27
	v_fmac_f32_e32 v18, v166, v26
	v_max_f32_e32 v28, 0, v28
	v_fmac_f32_e32 v18, v165, v27
	v_max_f32_e32 v29, 0, v29
	v_fmac_f32_e32 v18, v164, v28
	v_max_f32_e32 v30, 0, v30
	v_fmac_f32_e32 v18, v163, v29
	v_fmac_f32_e32 v18, v162, v30
	v_max_f32_e32 v19, 0, v31
	v_fmac_f32_e32 v18, v161, v19
	v_max_f32_e32 v19, 0, v32
	v_fmac_f32_e32 v18, v160, v19
	v_max_f32_e32 v19, 0, v33
	v_fmac_f32_e32 v18, v89, v19
	v_not_b32_e32 v19, v18
	v_or_b32_e32 v20, 0x80000000, v18
	v_cmp_gt_i32_e32 vcc, 0, v18
	s_nop 1
	v_cndmask_b32_e32 v18, v20, v19, vcc
	v_cmp_le_u32_e32 vcc, v128, v87
	s_nop 1
	v_cndmask_b32_e32 v227, 0, v18, vcc

.LBB0_536:
	s_or_b64 exec, exec, s[84:85]
	v_mfma_f32_32x32x16_bf16 v[18:33], v[38:41], v[58:61], 0
	v_mfma_f32_32x32x16_bf16 v[18:33], v[46:49], v[54:57], v[18:33]
	v_mfma_f32_32x32x16_bf16 v[18:33], v[34:37], v[50:53], v[18:33]
	v_mfma_f32_32x32x16_bf16 v[18:33], v[42:45], v[62:65], v[18:33]
	ds_read_b128 v[58:61], v74 offset:4096
	ds_read_b128 v[54:57], v75 offset:4096
	ds_read_b128 v[50:53], v76 offset:4096
	ds_read_b128 v[62:65], v77 offset:4096
	s_nop 8
	v_max_f32_e32 v18, 0, v18
	v_max_f32_e32 v19, 0, v19
	v_fma_f32 v18, v174, v18, 0
	v_max_f32_e32 v20, 0, v20
	v_fmac_f32_e32 v18, v173, v19
	v_max_f32_e32 v21, 0, v21
	v_fmac_f32_e32 v18, v172, v20
	v_max_f32_e32 v22, 0, v22
	v_fmac_f32_e32 v18, v171, v21
	v_max_f32_e32 v23, 0, v23
	v_fmac_f32_e32 v18, v170, v22
	v_max_f32_e32 v24, 0, v24
	v_fmac_f32_e32 v18, v169, v23
	v_max_f32_e32 v25, 0, v25
	v_fmac_f32_e32 v18, v168, v24
	v_max_f32_e32 v26, 0, v26
	v_fmac_f32_e32 v18, v167, v25
	v_max_f32_e32 v27, 0, v27
	v_fmac_f32_e32 v18, v166, v26
	v_max_f32_e32 v28, 0, v28
	v_fmac_f32_e32 v18, v165, v27
	v_max_f32_e32 v29, 0, v29
	v_fmac_f32_e32 v18, v164, v28
	v_max_f32_e32 v30, 0, v30
	v_fmac_f32_e32 v18, v163, v29
	v_fmac_f32_e32 v18, v162, v30
	v_max_f32_e32 v19, 0, v31
	v_fmac_f32_e32 v18, v161, v19
	v_max_f32_e32 v19, 0, v32
	v_fmac_f32_e32 v18, v160, v19
	v_max_f32_e32 v19, 0, v33
	v_fmac_f32_e32 v18, v89, v19
	v_not_b32_e32 v19, v18
	v_or_b32_e32 v20, 0x80000000, v18
	v_cmp_gt_i32_e32 vcc, 0, v18
	s_nop 1
	v_cndmask_b32_e32 v18, v20, v19, vcc
	v_cmp_le_u32_e32 vcc, v129, v87
	s_nop 1
	v_cndmask_b32_e32 v228, 0, v18, vcc

.LBB0_540:
	s_or_b64 exec, exec, s[84:85]
	v_mfma_f32_32x32x16_bf16 v[18:33], v[38:41], v[58:61], 0
	v_mfma_f32_32x32x16_bf16 v[18:33], v[46:49], v[54:57], v[18:33]
	v_mfma_f32_32x32x16_bf16 v[18:33], v[34:37], v[50:53], v[18:33]
	v_mfma_f32_32x32x16_bf16 v[18:33], v[42:45], v[62:65], v[18:33]
	ds_read_b128 v[58:61], v74 offset:8192
	ds_read_b128 v[54:57], v75 offset:8192
	ds_read_b128 v[50:53], v76 offset:8192
	ds_read_b128 v[62:65], v77 offset:8192
	s_nop 8
	v_max_f32_e32 v18, 0, v18
	v_max_f32_e32 v19, 0, v19
	v_fma_f32 v18, v174, v18, 0
	v_max_f32_e32 v20, 0, v20
	v_fmac_f32_e32 v18, v173, v19
	v_max_f32_e32 v21, 0, v21
	v_fmac_f32_e32 v18, v172, v20
	v_max_f32_e32 v22, 0, v22
	v_fmac_f32_e32 v18, v171, v21
	v_max_f32_e32 v23, 0, v23
	v_fmac_f32_e32 v18, v170, v22
	v_max_f32_e32 v24, 0, v24
	v_fmac_f32_e32 v18, v169, v23
	v_max_f32_e32 v25, 0, v25
	v_fmac_f32_e32 v18, v168, v24
	v_max_f32_e32 v26, 0, v26
	v_fmac_f32_e32 v18, v167, v25
	v_max_f32_e32 v27, 0, v27
	v_fmac_f32_e32 v18, v166, v26
	v_max_f32_e32 v28, 0, v28
	v_fmac_f32_e32 v18, v165, v27
	v_max_f32_e32 v29, 0, v29
	v_fmac_f32_e32 v18, v164, v28
	v_max_f32_e32 v30, 0, v30
	v_fmac_f32_e32 v18, v163, v29
	v_fmac_f32_e32 v18, v162, v30
	v_max_f32_e32 v19, 0, v31
	v_fmac_f32_e32 v18, v161, v19
	v_max_f32_e32 v19, 0, v32
	v_fmac_f32_e32 v18, v160, v19
	v_max_f32_e32 v19, 0, v33
	v_fmac_f32_e32 v18, v89, v19
	v_not_b32_e32 v19, v18
	v_or_b32_e32 v20, 0x80000000, v18
	v_cmp_gt_i32_e32 vcc, 0, v18
	s_nop 1
	v_cndmask_b32_e32 v18, v20, v19, vcc
	v_cmp_le_u32_e32 vcc, v130, v87
	s_nop 1
	v_cndmask_b32_e32 v229, 0, v18, vcc

.LBB0_544:
	s_or_b64 exec, exec, s[84:85]
	v_mfma_f32_32x32x16_bf16 v[18:33], v[38:41], v[58:61], 0
	v_mfma_f32_32x32x16_bf16 v[18:33], v[46:49], v[54:57], v[18:33]
	v_mfma_f32_32x32x16_bf16 v[18:33], v[34:37], v[50:53], v[18:33]
	v_mfma_f32_32x32x16_bf16 v[18:33], v[42:45], v[62:65], v[18:33]
	ds_read_b128 v[58:61], v74 offset:12288
	ds_read_b128 v[54:57], v75 offset:12288
	ds_read_b128 v[50:53], v76 offset:12288
	ds_read_b128 v[62:65], v77 offset:12288
	s_nop 8
	v_max_f32_e32 v18, 0, v18
	v_max_f32_e32 v19, 0, v19
	v_fma_f32 v18, v174, v18, 0
	v_max_f32_e32 v20, 0, v20
	v_fmac_f32_e32 v18, v173, v19
	v_max_f32_e32 v21, 0, v21
	v_fmac_f32_e32 v18, v172, v20
	v_max_f32_e32 v22, 0, v22
	v_fmac_f32_e32 v18, v171, v21
	v_max_f32_e32 v23, 0, v23
	v_fmac_f32_e32 v18, v170, v22
	v_max_f32_e32 v24, 0, v24
	v_fmac_f32_e32 v18, v169, v23
	v_max_f32_e32 v25, 0, v25
	v_fmac_f32_e32 v18, v168, v24
	v_max_f32_e32 v26, 0, v26
	v_fmac_f32_e32 v18, v167, v25
	v_max_f32_e32 v27, 0, v27
	v_fmac_f32_e32 v18, v166, v26
	v_max_f32_e32 v28, 0, v28
	v_fmac_f32_e32 v18, v165, v27
	v_max_f32_e32 v29, 0, v29
	v_fmac_f32_e32 v18, v164, v28
	v_max_f32_e32 v30, 0, v30
	v_fmac_f32_e32 v18, v163, v29
	v_fmac_f32_e32 v18, v162, v30
	v_max_f32_e32 v19, 0, v31
	v_fmac_f32_e32 v18, v161, v19
	v_max_f32_e32 v19, 0, v32
	v_fmac_f32_e32 v18, v160, v19
	v_max_f32_e32 v19, 0, v33
	v_fmac_f32_e32 v18, v89, v19
	v_not_b32_e32 v19, v18
	v_or_b32_e32 v20, 0x80000000, v18
	v_cmp_gt_i32_e32 vcc, 0, v18
	s_nop 1
	v_cndmask_b32_e32 v18, v20, v19, vcc
	v_cmp_le_u32_e32 vcc, v131, v87
	s_nop 1
	v_cndmask_b32_e32 v230, 0, v18, vcc

.LBB0_548:
	s_or_b64 exec, exec, s[84:85]
	v_mfma_f32_32x32x16_bf16 v[18:33], v[38:41], v[58:61], 0
	v_mfma_f32_32x32x16_bf16 v[18:33], v[46:49], v[54:57], v[18:33]
	v_mfma_f32_32x32x16_bf16 v[18:33], v[34:37], v[50:53], v[18:33]
	v_mfma_f32_32x32x16_bf16 v[18:33], v[42:45], v[62:65], v[18:33]
	ds_read_b128 v[58:61], v74 offset:16384
	ds_read_b128 v[54:57], v75 offset:16384
	ds_read_b128 v[50:53], v76 offset:16384
	ds_read_b128 v[62:65], v77 offset:16384
	s_nop 8
	v_max_f32_e32 v18, 0, v18
	v_max_f32_e32 v19, 0, v19
	v_fma_f32 v18, v174, v18, 0
	v_max_f32_e32 v20, 0, v20
	v_fmac_f32_e32 v18, v173, v19
	v_max_f32_e32 v21, 0, v21
	v_fmac_f32_e32 v18, v172, v20
	v_max_f32_e32 v22, 0, v22
	v_fmac_f32_e32 v18, v171, v21
	v_max_f32_e32 v23, 0, v23
	v_fmac_f32_e32 v18, v170, v22
	v_max_f32_e32 v24, 0, v24
	v_fmac_f32_e32 v18, v169, v23
	v_max_f32_e32 v25, 0, v25
	v_fmac_f32_e32 v18, v168, v24
	v_max_f32_e32 v26, 0, v26
	v_fmac_f32_e32 v18, v167, v25
	v_max_f32_e32 v27, 0, v27
	v_fmac_f32_e32 v18, v166, v26
	v_max_f32_e32 v28, 0, v28
	v_fmac_f32_e32 v18, v165, v27
	v_max_f32_e32 v29, 0, v29
	v_fmac_f32_e32 v18, v164, v28
	v_max_f32_e32 v30, 0, v30
	v_fmac_f32_e32 v18, v163, v29
	v_fmac_f32_e32 v18, v162, v30
	v_max_f32_e32 v19, 0, v31
	v_fmac_f32_e32 v18, v161, v19
	v_max_f32_e32 v19, 0, v32
	v_fmac_f32_e32 v18, v160, v19
	v_max_f32_e32 v19, 0, v33
	v_fmac_f32_e32 v18, v89, v19
	v_not_b32_e32 v19, v18
	v_or_b32_e32 v20, 0x80000000, v18
	v_cmp_gt_i32_e32 vcc, 0, v18
	s_nop 1
	v_cndmask_b32_e32 v18, v20, v19, vcc
	v_cmp_le_u32_e32 vcc, v132, v87
	s_nop 1
	v_cndmask_b32_e32 v231, 0, v18, vcc

.LBB0_552:
	s_or_b64 exec, exec, s[84:85]
	v_mfma_f32_32x32x16_bf16 v[18:33], v[38:41], v[58:61], 0
	v_mfma_f32_32x32x16_bf16 v[18:33], v[46:49], v[54:57], v[18:33]
	v_mfma_f32_32x32x16_bf16 v[18:33], v[34:37], v[50:53], v[18:33]
	v_mfma_f32_32x32x16_bf16 v[18:33], v[42:45], v[62:65], v[18:33]
	ds_read_b128 v[58:61], v74 offset:20480
	ds_read_b128 v[54:57], v75 offset:20480
	ds_read_b128 v[50:53], v76 offset:20480
	ds_read_b128 v[62:65], v77 offset:20480
	s_nop 8
	v_max_f32_e32 v18, 0, v18
	v_max_f32_e32 v19, 0, v19
	v_fma_f32 v18, v174, v18, 0
	v_max_f32_e32 v20, 0, v20
	v_fmac_f32_e32 v18, v173, v19
	v_max_f32_e32 v21, 0, v21
	v_fmac_f32_e32 v18, v172, v20
	v_max_f32_e32 v22, 0, v22
	v_fmac_f32_e32 v18, v171, v21
	v_max_f32_e32 v23, 0, v23
	v_fmac_f32_e32 v18, v170, v22
	v_max_f32_e32 v24, 0, v24
	v_fmac_f32_e32 v18, v169, v23
	v_max_f32_e32 v25, 0, v25
	v_fmac_f32_e32 v18, v168, v24
	v_max_f32_e32 v26, 0, v26
	v_fmac_f32_e32 v18, v167, v25
	v_max_f32_e32 v27, 0, v27
	v_fmac_f32_e32 v18, v166, v26
	v_max_f32_e32 v28, 0, v28
	v_fmac_f32_e32 v18, v165, v27
	v_max_f32_e32 v29, 0, v29
	v_fmac_f32_e32 v18, v164, v28
	v_max_f32_e32 v30, 0, v30
	v_fmac_f32_e32 v18, v163, v29
	v_fmac_f32_e32 v18, v162, v30
	v_max_f32_e32 v19, 0, v31
	v_fmac_f32_e32 v18, v161, v19
	v_max_f32_e32 v19, 0, v32
	v_fmac_f32_e32 v18, v160, v19
	v_max_f32_e32 v19, 0, v33
	v_fmac_f32_e32 v18, v89, v19
	v_not_b32_e32 v19, v18
	v_or_b32_e32 v20, 0x80000000, v18
	v_cmp_gt_i32_e32 vcc, 0, v18
	s_nop 1
	v_cndmask_b32_e32 v18, v20, v19, vcc
	v_cmp_le_u32_e32 vcc, v133, v87
	s_nop 1
	v_cndmask_b32_e32 v232, 0, v18, vcc

.LBB0_556:
	s_or_b64 exec, exec, s[84:85]
	v_mfma_f32_32x32x16_bf16 v[18:33], v[38:41], v[58:61], 0
	v_mfma_f32_32x32x16_bf16 v[18:33], v[46:49], v[54:57], v[18:33]
	v_mfma_f32_32x32x16_bf16 v[18:33], v[34:37], v[50:53], v[18:33]
	v_mfma_f32_32x32x16_bf16 v[18:33], v[42:45], v[62:65], v[18:33]
	ds_read_b128 v[58:61], v74 offset:24576
	ds_read_b128 v[54:57], v75 offset:24576
	ds_read_b128 v[50:53], v76 offset:24576
	ds_read_b128 v[62:65], v77 offset:24576
	s_nop 8
	v_max_f32_e32 v18, 0, v18
	v_max_f32_e32 v19, 0, v19
	v_fma_f32 v18, v174, v18, 0
	v_max_f32_e32 v20, 0, v20
	v_fmac_f32_e32 v18, v173, v19
	v_max_f32_e32 v21, 0, v21
	v_fmac_f32_e32 v18, v172, v20
	v_max_f32_e32 v22, 0, v22
	v_fmac_f32_e32 v18, v171, v21
	v_max_f32_e32 v23, 0, v23
	v_fmac_f32_e32 v18, v170, v22
	v_max_f32_e32 v24, 0, v24
	v_fmac_f32_e32 v18, v169, v23
	v_max_f32_e32 v25, 0, v25
	v_fmac_f32_e32 v18, v168, v24
	v_max_f32_e32 v26, 0, v26
	v_fmac_f32_e32 v18, v167, v25
	v_max_f32_e32 v27, 0, v27
	v_fmac_f32_e32 v18, v166, v26
	v_max_f32_e32 v28, 0, v28
	v_fmac_f32_e32 v18, v165, v27
	v_max_f32_e32 v29, 0, v29
	v_fmac_f32_e32 v18, v164, v28
	v_max_f32_e32 v30, 0, v30
	v_fmac_f32_e32 v18, v163, v29
	v_fmac_f32_e32 v18, v162, v30
	v_max_f32_e32 v19, 0, v31
	v_fmac_f32_e32 v18, v161, v19
	v_max_f32_e32 v19, 0, v32
	v_fmac_f32_e32 v18, v160, v19
	v_max_f32_e32 v19, 0, v33
	v_fmac_f32_e32 v18, v89, v19
	v_not_b32_e32 v19, v18
	v_or_b32_e32 v20, 0x80000000, v18
	v_cmp_gt_i32_e32 vcc, 0, v18
	s_nop 1
	v_cndmask_b32_e32 v18, v20, v19, vcc
	v_cmp_le_u32_e32 vcc, v134, v87
	s_nop 1
	v_cndmask_b32_e32 v233, 0, v18, vcc

.LBB0_560:
	s_or_b64 exec, exec, s[84:85]
	v_mfma_f32_32x32x16_bf16 v[18:33], v[38:41], v[58:61], 0
	v_mfma_f32_32x32x16_bf16 v[18:33], v[46:49], v[54:57], v[18:33]
	v_mfma_f32_32x32x16_bf16 v[18:33], v[34:37], v[50:53], v[18:33]
	v_mfma_f32_32x32x16_bf16 v[18:33], v[42:45], v[62:65], v[18:33]
	ds_read_b128 v[58:61], v74 offset:28672
	ds_read_b128 v[54:57], v75 offset:28672
	ds_read_b128 v[50:53], v76 offset:28672
	ds_read_b128 v[62:65], v77 offset:28672
	s_nop 8
	v_max_f32_e32 v18, 0, v18
	v_max_f32_e32 v19, 0, v19
	v_fma_f32 v18, v174, v18, 0
	v_max_f32_e32 v20, 0, v20
	v_fmac_f32_e32 v18, v173, v19
	v_max_f32_e32 v21, 0, v21
	v_fmac_f32_e32 v18, v172, v20
	v_max_f32_e32 v22, 0, v22
	v_fmac_f32_e32 v18, v171, v21
	v_max_f32_e32 v23, 0, v23
	v_fmac_f32_e32 v18, v170, v22
	v_max_f32_e32 v24, 0, v24
	v_fmac_f32_e32 v18, v169, v23
	v_max_f32_e32 v25, 0, v25
	v_fmac_f32_e32 v18, v168, v24
	v_max_f32_e32 v26, 0, v26
	v_fmac_f32_e32 v18, v167, v25
	v_max_f32_e32 v27, 0, v27
	v_fmac_f32_e32 v18, v166, v26
	v_max_f32_e32 v28, 0, v28
	v_fmac_f32_e32 v18, v165, v27
	v_max_f32_e32 v29, 0, v29
	v_fmac_f32_e32 v18, v164, v28
	v_max_f32_e32 v30, 0, v30
	v_fmac_f32_e32 v18, v163, v29
	v_fmac_f32_e32 v18, v162, v30
	v_max_f32_e32 v19, 0, v31
	v_fmac_f32_e32 v18, v161, v19
	v_max_f32_e32 v19, 0, v32
	v_fmac_f32_e32 v18, v160, v19
	v_max_f32_e32 v19, 0, v33
	v_fmac_f32_e32 v18, v89, v19
	v_not_b32_e32 v19, v18
	v_or_b32_e32 v20, 0x80000000, v18
	v_cmp_gt_i32_e32 vcc, 0, v18
	s_nop 1
	v_cndmask_b32_e32 v18, v20, v19, vcc
	v_cmp_le_u32_e32 vcc, v135, v87
	s_nop 1
	v_cndmask_b32_e32 v234, 0, v18, vcc
.LBB0_561:
	s_or_b64 exec, exec, s[82:83]
	s_movk_i32 s2, 0x51f
	v_cmp_lt_u32_e32 vcc, s2, v177
	v_mov_b32_e32 v235, 0
	s_and_saveexec_b64 s[82:83], vcc
	s_cbranch_execz .LBB0_565
	s_movk_i32 s2, 0x53f
	s_waitcnt lgkmcnt(0)
	s_waitcnt vmcnt(0)
	s_barrier
	v_cmp_le_u32_e32 vcc, v79, v80
	s_and_b64 vcc, exec, vcc
	s_cbranch_vccz .Lidxd_s5
	s_nop 0
	global_load_lds_dwordx4 v72, s[100:101]
	s_add_u32 m0, m0, 0x400
	s_add_u32 s100, s100, 0x1a000
	s_addc_u32 s101, s101, 0
	s_nop 0
	global_load_lds_dwordx4 v73, s[100:101]
	s_add_u32 m0, m0, 0x400
	s_add_u32 s100, s100, 0x1a000
	s_addc_u32 s101, s101, 0
	s_nop 0
	global_load_lds_dwordx4 v72, s[100:101]
	s_add_u32 m0, m0, 0x400
	s_add_u32 s100, s100, 0x1a000
	s_addc_u32 s101, s101, 0
	s_nop 0
	global_load_lds_dwordx4 v73, s[100:101]
	s_add_u32 m0, m0, 0x400
	s_add_u32 s100, s100, 0x1a000
	s_addc_u32 s101, s101, 0
	s_add_u32 m0, m0, 0x7000
	s_add_u32 s100, s100, 0x2d8000
	s_addc_u32 s101, s101, 0
	v_add_u32_e32 v79, 8, v79

.LBB0_564:
	s_or_b64 exec, exec, s[84:85]
	v_mfma_f32_32x32x16_bf16 v[18:33], v[38:41], v[58:61], 0
	v_mfma_f32_32x32x16_bf16 v[18:33], v[46:49], v[54:57], v[18:33]
	v_mfma_f32_32x32x16_bf16 v[18:33], v[34:37], v[50:53], v[18:33]
	v_mfma_f32_32x32x16_bf16 v[18:33], v[42:45], v[62:65], v[18:33]
	ds_read_b128 v[58:61], v74 offset:32768
	ds_read_b128 v[54:57], v75 offset:32768
	ds_read_b128 v[50:53], v76 offset:32768
	ds_read_b128 v[62:65], v77 offset:32768
	s_nop 8
	v_max_f32_e32 v18, 0, v18
	v_max_f32_e32 v19, 0, v19
	v_fma_f32 v18, v174, v18, 0
	v_max_f32_e32 v20, 0, v20
	v_fmac_f32_e32 v18, v173, v19
	v_max_f32_e32 v21, 0, v21
	v_fmac_f32_e32 v18, v172, v20
	v_max_f32_e32 v22, 0, v22
	v_fmac_f32_e32 v18, v171, v21
	v_max_f32_e32 v23, 0, v23
	v_fmac_f32_e32 v18, v170, v22
	v_max_f32_e32 v24, 0, v24
	v_fmac_f32_e32 v18, v169, v23
	v_max_f32_e32 v25, 0, v25
	v_fmac_f32_e32 v18, v168, v24
	v_max_f32_e32 v26, 0, v26
	v_fmac_f32_e32 v18, v167, v25
	v_max_f32_e32 v27, 0, v27
	v_fmac_f32_e32 v18, v166, v26
	v_max_f32_e32 v28, 0, v28
	v_fmac_f32_e32 v18, v165, v27
	v_max_f32_e32 v29, 0, v29
	v_fmac_f32_e32 v18, v164, v28
	v_max_f32_e32 v30, 0, v30
	v_fmac_f32_e32 v18, v163, v29
	v_fmac_f32_e32 v18, v162, v30
	v_max_f32_e32 v19, 0, v31
	v_fmac_f32_e32 v18, v161, v19
	v_max_f32_e32 v19, 0, v32
	v_fmac_f32_e32 v18, v160, v19
	v_max_f32_e32 v19, 0, v33
	v_fmac_f32_e32 v18, v89, v19
	v_not_b32_e32 v19, v18
	v_or_b32_e32 v20, 0x80000000, v18
	v_cmp_gt_i32_e32 vcc, 0, v18
	s_nop 1
	v_cndmask_b32_e32 v18, v20, v19, vcc
	v_cmp_le_u32_e32 vcc, v136, v87
	s_nop 1
	v_cndmask_b32_e32 v235, 0, v18, vcc

.LBB0_568:
	s_or_b64 exec, exec, s[84:85]
	v_mfma_f32_32x32x16_bf16 v[18:33], v[38:41], v[58:61], 0
	v_mfma_f32_32x32x16_bf16 v[18:33], v[46:49], v[54:57], v[18:33]
	v_mfma_f32_32x32x16_bf16 v[18:33], v[34:37], v[50:53], v[18:33]
	v_mfma_f32_32x32x16_bf16 v[18:33], v[42:45], v[62:65], v[18:33]
	ds_read_b128 v[58:61], v74 offset:36864
	ds_read_b128 v[54:57], v75 offset:36864
	ds_read_b128 v[50:53], v76 offset:36864
	ds_read_b128 v[62:65], v77 offset:36864
	s_nop 8
	v_max_f32_e32 v18, 0, v18
	v_max_f32_e32 v19, 0, v19
	v_fma_f32 v18, v174, v18, 0
	v_max_f32_e32 v20, 0, v20
	v_fmac_f32_e32 v18, v173, v19
	v_max_f32_e32 v21, 0, v21
	v_fmac_f32_e32 v18, v172, v20
	v_max_f32_e32 v22, 0, v22
	v_fmac_f32_e32 v18, v171, v21
	v_max_f32_e32 v23, 0, v23
	v_fmac_f32_e32 v18, v170, v22
	v_max_f32_e32 v24, 0, v24
	v_fmac_f32_e32 v18, v169, v23
	v_max_f32_e32 v25, 0, v25
	v_fmac_f32_e32 v18, v168, v24
	v_max_f32_e32 v26, 0, v26
	v_fmac_f32_e32 v18, v167, v25
	v_max_f32_e32 v27, 0, v27
	v_fmac_f32_e32 v18, v166, v26
	v_max_f32_e32 v28, 0, v28
	v_fmac_f32_e32 v18, v165, v27
	v_max_f32_e32 v29, 0, v29
	v_fmac_f32_e32 v18, v164, v28
	v_max_f32_e32 v30, 0, v30
	v_fmac_f32_e32 v18, v163, v29
	v_fmac_f32_e32 v18, v162, v30
	v_max_f32_e32 v19, 0, v31
	v_fmac_f32_e32 v18, v161, v19
	v_max_f32_e32 v19, 0, v32
	v_fmac_f32_e32 v18, v160, v19
	v_max_f32_e32 v19, 0, v33
	v_fmac_f32_e32 v18, v89, v19
	v_not_b32_e32 v19, v18
	v_or_b32_e32 v20, 0x80000000, v18
	v_cmp_gt_i32_e32 vcc, 0, v18
	s_nop 1
	v_cndmask_b32_e32 v18, v20, v19, vcc
	v_cmp_le_u32_e32 vcc, v137, v87
	s_nop 1
	v_cndmask_b32_e32 v236, 0, v18, vcc

.LBB0_572:
	s_or_b64 exec, exec, s[84:85]
	v_mfma_f32_32x32x16_bf16 v[18:33], v[38:41], v[58:61], 0
	v_mfma_f32_32x32x16_bf16 v[18:33], v[46:49], v[54:57], v[18:33]
	v_mfma_f32_32x32x16_bf16 v[18:33], v[34:37], v[50:53], v[18:33]
	v_mfma_f32_32x32x16_bf16 v[18:33], v[42:45], v[62:65], v[18:33]
	ds_read_b128 v[58:61], v74 offset:40960
	ds_read_b128 v[54:57], v75 offset:40960
	ds_read_b128 v[50:53], v76 offset:40960
	ds_read_b128 v[62:65], v77 offset:40960
	s_nop 8
	v_max_f32_e32 v18, 0, v18
	v_max_f32_e32 v19, 0, v19
	v_fma_f32 v18, v174, v18, 0
	v_max_f32_e32 v20, 0, v20
	v_fmac_f32_e32 v18, v173, v19
	v_max_f32_e32 v21, 0, v21
	v_fmac_f32_e32 v18, v172, v20
	v_max_f32_e32 v22, 0, v22
	v_fmac_f32_e32 v18, v171, v21
	v_max_f32_e32 v23, 0, v23
	v_fmac_f32_e32 v18, v170, v22
	v_max_f32_e32 v24, 0, v24
	v_fmac_f32_e32 v18, v169, v23
	v_max_f32_e32 v25, 0, v25
	v_fmac_f32_e32 v18, v168, v24
	v_max_f32_e32 v26, 0, v26
	v_fmac_f32_e32 v18, v167, v25
	v_max_f32_e32 v27, 0, v27
	v_fmac_f32_e32 v18, v166, v26
	v_max_f32_e32 v28, 0, v28
	v_fmac_f32_e32 v18, v165, v27
	v_max_f32_e32 v29, 0, v29
	v_fmac_f32_e32 v18, v164, v28
	v_max_f32_e32 v30, 0, v30
	v_fmac_f32_e32 v18, v163, v29
	v_fmac_f32_e32 v18, v162, v30
	v_max_f32_e32 v19, 0, v31
	v_fmac_f32_e32 v18, v161, v19
	v_max_f32_e32 v19, 0, v32
	v_fmac_f32_e32 v18, v160, v19
	v_max_f32_e32 v19, 0, v33
	v_fmac_f32_e32 v18, v89, v19
	v_not_b32_e32 v19, v18
	v_or_b32_e32 v20, 0x80000000, v18
	v_cmp_gt_i32_e32 vcc, 0, v18
	s_nop 1
	v_cndmask_b32_e32 v18, v20, v19, vcc
	v_cmp_le_u32_e32 vcc, v138, v87
	s_nop 1
	v_cndmask_b32_e32 v237, 0, v18, vcc

.LBB0_576:
	s_or_b64 exec, exec, s[84:85]
	v_mfma_f32_32x32x16_bf16 v[18:33], v[38:41], v[58:61], 0
	v_mfma_f32_32x32x16_bf16 v[18:33], v[46:49], v[54:57], v[18:33]
	v_mfma_f32_32x32x16_bf16 v[18:33], v[34:37], v[50:53], v[18:33]
	v_mfma_f32_32x32x16_bf16 v[18:33], v[42:45], v[62:65], v[18:33]
	ds_read_b128 v[58:61], v74 offset:45056
	ds_read_b128 v[54:57], v75 offset:45056
	ds_read_b128 v[50:53], v76 offset:45056
	ds_read_b128 v[62:65], v77 offset:45056
	s_nop 8
	v_max_f32_e32 v18, 0, v18
	v_max_f32_e32 v19, 0, v19
	v_fma_f32 v18, v174, v18, 0
	v_max_f32_e32 v20, 0, v20
	v_fmac_f32_e32 v18, v173, v19
	v_max_f32_e32 v21, 0, v21
	v_fmac_f32_e32 v18, v172, v20
	v_max_f32_e32 v22, 0, v22
	v_fmac_f32_e32 v18, v171, v21
	v_max_f32_e32 v23, 0, v23
	v_fmac_f32_e32 v18, v170, v22
	v_max_f32_e32 v24, 0, v24
	v_fmac_f32_e32 v18, v169, v23
	v_max_f32_e32 v25, 0, v25
	v_fmac_f32_e32 v18, v168, v24
	v_max_f32_e32 v26, 0, v26
	v_fmac_f32_e32 v18, v167, v25
	v_max_f32_e32 v27, 0, v27
	v_fmac_f32_e32 v18, v166, v26
	v_max_f32_e32 v28, 0, v28
	v_fmac_f32_e32 v18, v165, v27
	v_max_f32_e32 v29, 0, v29
	v_fmac_f32_e32 v18, v164, v28
	v_max_f32_e32 v30, 0, v30
	v_fmac_f32_e32 v18, v163, v29
	v_fmac_f32_e32 v18, v162, v30
	v_max_f32_e32 v19, 0, v31
	v_fmac_f32_e32 v18, v161, v19
	v_max_f32_e32 v19, 0, v32
	v_fmac_f32_e32 v18, v160, v19
	v_max_f32_e32 v19, 0, v33
	v_fmac_f32_e32 v18, v89, v19
	v_not_b32_e32 v19, v18
	v_or_b32_e32 v20, 0x80000000, v18
	v_cmp_gt_i32_e32 vcc, 0, v18
	s_nop 1
	v_cndmask_b32_e32 v18, v20, v19, vcc
	v_cmp_le_u32_e32 vcc, v139, v87
	s_nop 1
	v_cndmask_b32_e32 v238, 0, v18, vcc

.LBB0_580:
	s_or_b64 exec, exec, s[84:85]
	v_mfma_f32_32x32x16_bf16 v[18:33], v[38:41], v[58:61], 0
	v_mfma_f32_32x32x16_bf16 v[18:33], v[46:49], v[54:57], v[18:33]
	v_mfma_f32_32x32x16_bf16 v[18:33], v[34:37], v[50:53], v[18:33]
	v_mfma_f32_32x32x16_bf16 v[18:33], v[42:45], v[62:65], v[18:33]
	ds_read_b128 v[58:61], v74 offset:49152
	ds_read_b128 v[54:57], v75 offset:49152
	ds_read_b128 v[50:53], v76 offset:49152
	ds_read_b128 v[62:65], v77 offset:49152
	s_nop 8
	v_max_f32_e32 v18, 0, v18
	v_max_f32_e32 v19, 0, v19
	v_fma_f32 v18, v174, v18, 0
	v_max_f32_e32 v20, 0, v20
	v_fmac_f32_e32 v18, v173, v19
	v_max_f32_e32 v21, 0, v21
	v_fmac_f32_e32 v18, v172, v20
	v_max_f32_e32 v22, 0, v22
	v_fmac_f32_e32 v18, v171, v21
	v_max_f32_e32 v23, 0, v23
	v_fmac_f32_e32 v18, v170, v22
	v_max_f32_e32 v24, 0, v24
	v_fmac_f32_e32 v18, v169, v23
	v_max_f32_e32 v25, 0, v25
	v_fmac_f32_e32 v18, v168, v24
	v_max_f32_e32 v26, 0, v26
	v_fmac_f32_e32 v18, v167, v25
	v_max_f32_e32 v27, 0, v27
	v_fmac_f32_e32 v18, v166, v26
	v_max_f32_e32 v28, 0, v28
	v_fmac_f32_e32 v18, v165, v27
	v_max_f32_e32 v29, 0, v29
	v_fmac_f32_e32 v18, v164, v28
	v_max_f32_e32 v30, 0, v30
	v_fmac_f32_e32 v18, v163, v29
	v_fmac_f32_e32 v18, v162, v30
	v_max_f32_e32 v19, 0, v31
	v_fmac_f32_e32 v18, v161, v19
	v_max_f32_e32 v19, 0, v32
	v_fmac_f32_e32 v18, v160, v19
	v_max_f32_e32 v19, 0, v33
	v_fmac_f32_e32 v18, v89, v19
	v_not_b32_e32 v19, v18
	v_or_b32_e32 v20, 0x80000000, v18
	v_cmp_gt_i32_e32 vcc, 0, v18
	s_nop 1
	v_cndmask_b32_e32 v18, v20, v19, vcc
	v_cmp_le_u32_e32 vcc, v140, v87
	s_nop 1
	v_cndmask_b32_e32 v239, 0, v18, vcc

.LBB0_584:
	s_or_b64 exec, exec, s[84:85]
	v_mfma_f32_32x32x16_bf16 v[18:33], v[38:41], v[58:61], 0
	v_mfma_f32_32x32x16_bf16 v[18:33], v[46:49], v[54:57], v[18:33]
	v_mfma_f32_32x32x16_bf16 v[18:33], v[34:37], v[50:53], v[18:33]
	v_mfma_f32_32x32x16_bf16 v[18:33], v[42:45], v[62:65], v[18:33]
	ds_read_b128 v[58:61], v74 offset:53248
	ds_read_b128 v[54:57], v75 offset:53248
	ds_read_b128 v[50:53], v76 offset:53248
	ds_read_b128 v[62:65], v77 offset:53248
	s_nop 8
	v_max_f32_e32 v18, 0, v18
	v_max_f32_e32 v19, 0, v19
	v_fma_f32 v18, v174, v18, 0
	v_max_f32_e32 v20, 0, v20
	v_fmac_f32_e32 v18, v173, v19
	v_max_f32_e32 v21, 0, v21
	v_fmac_f32_e32 v18, v172, v20
	v_max_f32_e32 v22, 0, v22
	v_fmac_f32_e32 v18, v171, v21
	v_max_f32_e32 v23, 0, v23
	v_fmac_f32_e32 v18, v170, v22
	v_max_f32_e32 v24, 0, v24
	v_fmac_f32_e32 v18, v169, v23
	v_max_f32_e32 v25, 0, v25
	v_fmac_f32_e32 v18, v168, v24
	v_max_f32_e32 v26, 0, v26
	v_fmac_f32_e32 v18, v167, v25
	v_max_f32_e32 v27, 0, v27
	v_fmac_f32_e32 v18, v166, v26
	v_max_f32_e32 v28, 0, v28
	v_fmac_f32_e32 v18, v165, v27
	v_max_f32_e32 v29, 0, v29
	v_fmac_f32_e32 v18, v164, v28
	v_max_f32_e32 v30, 0, v30
	v_fmac_f32_e32 v18, v163, v29
	v_fmac_f32_e32 v18, v162, v30
	v_max_f32_e32 v19, 0, v31
	v_fmac_f32_e32 v18, v161, v19
	v_max_f32_e32 v19, 0, v32
	v_fmac_f32_e32 v18, v160, v19
	v_max_f32_e32 v19, 0, v33
	v_fmac_f32_e32 v18, v89, v19
	v_not_b32_e32 v19, v18
	v_or_b32_e32 v20, 0x80000000, v18
	v_cmp_gt_i32_e32 vcc, 0, v18
	s_nop 1
	v_cndmask_b32_e32 v18, v20, v19, vcc
	v_cmp_le_u32_e32 vcc, v141, v87
	s_nop 1
	v_cndmask_b32_e32 v240, 0, v18, vcc

.LBB0_588:
	s_or_b64 exec, exec, s[84:85]
	v_mfma_f32_32x32x16_bf16 v[18:33], v[38:41], v[58:61], 0
	v_mfma_f32_32x32x16_bf16 v[18:33], v[46:49], v[54:57], v[18:33]
	v_mfma_f32_32x32x16_bf16 v[18:33], v[34:37], v[50:53], v[18:33]
	v_mfma_f32_32x32x16_bf16 v[18:33], v[42:45], v[62:65], v[18:33]
	ds_read_b128 v[58:61], v74 offset:57344
	ds_read_b128 v[54:57], v75 offset:57344
	ds_read_b128 v[50:53], v76 offset:57344
	ds_read_b128 v[62:65], v77 offset:57344
	s_nop 8
	v_max_f32_e32 v18, 0, v18
	v_max_f32_e32 v19, 0, v19
	v_fma_f32 v18, v174, v18, 0
	v_max_f32_e32 v20, 0, v20
	v_fmac_f32_e32 v18, v173, v19
	v_max_f32_e32 v21, 0, v21
	v_fmac_f32_e32 v18, v172, v20
	v_max_f32_e32 v22, 0, v22
	v_fmac_f32_e32 v18, v171, v21
	v_max_f32_e32 v23, 0, v23
	v_fmac_f32_e32 v18, v170, v22
	v_max_f32_e32 v24, 0, v24
	v_fmac_f32_e32 v18, v169, v23
	v_max_f32_e32 v25, 0, v25
	v_fmac_f32_e32 v18, v168, v24
	v_max_f32_e32 v26, 0, v26
	v_fmac_f32_e32 v18, v167, v25
	v_max_f32_e32 v27, 0, v27
	v_fmac_f32_e32 v18, v166, v26
	v_max_f32_e32 v28, 0, v28
	v_fmac_f32_e32 v18, v165, v27
	v_max_f32_e32 v29, 0, v29
	v_fmac_f32_e32 v18, v164, v28
	v_max_f32_e32 v30, 0, v30
	v_fmac_f32_e32 v18, v163, v29
	v_fmac_f32_e32 v18, v162, v30
	v_max_f32_e32 v19, 0, v31
	v_fmac_f32_e32 v18, v161, v19
	v_max_f32_e32 v19, 0, v32
	v_fmac_f32_e32 v18, v160, v19
	v_max_f32_e32 v19, 0, v33
	v_fmac_f32_e32 v18, v89, v19
	v_not_b32_e32 v19, v18
	v_or_b32_e32 v20, 0x80000000, v18
	v_cmp_gt_i32_e32 vcc, 0, v18
	s_nop 1
	v_cndmask_b32_e32 v18, v20, v19, vcc
	v_cmp_le_u32_e32 vcc, v142, v87
	s_nop 1
	v_cndmask_b32_e32 v241, 0, v18, vcc

.LBB0_592:
	s_or_b64 exec, exec, s[84:85]
	v_mfma_f32_32x32x16_bf16 v[18:33], v[38:41], v[58:61], 0
	v_mfma_f32_32x32x16_bf16 v[18:33], v[46:49], v[54:57], v[18:33]
	v_mfma_f32_32x32x16_bf16 v[18:33], v[34:37], v[50:53], v[18:33]
	v_mfma_f32_32x32x16_bf16 v[18:33], v[42:45], v[62:65], v[18:33]
	ds_read_b128 v[58:61], v74 offset:61440
	ds_read_b128 v[54:57], v75 offset:61440
	ds_read_b128 v[50:53], v76 offset:61440
	ds_read_b128 v[62:65], v77 offset:61440
	s_nop 8
	v_max_f32_e32 v18, 0, v18
	v_max_f32_e32 v19, 0, v19
	v_fma_f32 v18, v174, v18, 0
	v_max_f32_e32 v20, 0, v20
	v_fmac_f32_e32 v18, v173, v19
	v_max_f32_e32 v21, 0, v21
	v_fmac_f32_e32 v18, v172, v20
	v_max_f32_e32 v22, 0, v22
	v_fmac_f32_e32 v18, v171, v21
	v_max_f32_e32 v23, 0, v23
	v_fmac_f32_e32 v18, v170, v22
	v_max_f32_e32 v24, 0, v24
	v_fmac_f32_e32 v18, v169, v23
	v_max_f32_e32 v25, 0, v25
	v_fmac_f32_e32 v18, v168, v24
	v_max_f32_e32 v26, 0, v26
	v_fmac_f32_e32 v18, v167, v25
	v_max_f32_e32 v27, 0, v27
	v_fmac_f32_e32 v18, v166, v26
	v_max_f32_e32 v28, 0, v28
	v_fmac_f32_e32 v18, v165, v27
	v_max_f32_e32 v29, 0, v29
	v_fmac_f32_e32 v18, v164, v28
	v_max_f32_e32 v30, 0, v30
	v_fmac_f32_e32 v18, v163, v29
	v_fmac_f32_e32 v18, v162, v30
	v_max_f32_e32 v19, 0, v31
	v_fmac_f32_e32 v18, v161, v19
	v_max_f32_e32 v19, 0, v32
	v_fmac_f32_e32 v18, v160, v19
	v_max_f32_e32 v19, 0, v33
	v_fmac_f32_e32 v18, v89, v19
	v_not_b32_e32 v19, v18
	v_or_b32_e32 v20, 0x80000000, v18
	v_cmp_gt_i32_e32 vcc, 0, v18
	s_nop 1
	v_cndmask_b32_e32 v18, v20, v19, vcc
	v_cmp_le_u32_e32 vcc, v143, v87
	s_nop 1
	v_cndmask_b32_e32 v242, 0, v18, vcc
.LBB0_593:
	s_or_b64 exec, exec, s[82:83]
	s_movk_i32 s2, 0x61f
	v_cmp_lt_u32_e32 vcc, s2, v177
	v_mov_b32_e32 v243, 0
	s_and_saveexec_b64 s[82:83], vcc
	s_cbranch_execz .LBB0_597
	s_movk_i32 s2, 0x63f
	s_waitcnt lgkmcnt(0)
	s_waitcnt vmcnt(0)
	s_barrier
	v_cmp_le_u32_e32 vcc, v79, v80
	s_and_b64 vcc, exec, vcc
	s_cbranch_vccz .Lidxd_s6
	s_nop 0
	global_load_lds_dwordx4 v72, s[100:101]
	s_add_u32 m0, m0, 0x400
	s_add_u32 s100, s100, 0x1a000
	s_addc_u32 s101, s101, 0
	s_nop 0
	global_load_lds_dwordx4 v73, s[100:101]
	s_add_u32 m0, m0, 0x400
	s_add_u32 s100, s100, 0x1a000
	s_addc_u32 s101, s101, 0
	s_nop 0
	global_load_lds_dwordx4 v72, s[100:101]
	s_add_u32 m0, m0, 0x400
	s_add_u32 s100, s100, 0x1a000
	s_addc_u32 s101, s101, 0
	s_nop 0
	global_load_lds_dwordx4 v73, s[100:101]
	s_add_u32 m0, m0, 0x400
	s_add_u32 s100, s100, 0x1a000
	s_addc_u32 s101, s101, 0
	s_sub_u32 m0, m0, 0x9000
	s_add_u32 s100, s100, 0x2d8000
	s_addc_u32 s101, s101, 0
	v_add_u32_e32 v79, 8, v79

.LBB0_596:
	s_or_b64 exec, exec, s[84:85]
	v_mfma_f32_32x32x16_bf16 v[18:33], v[38:41], v[58:61], 0
	v_mfma_f32_32x32x16_bf16 v[18:33], v[46:49], v[54:57], v[18:33]
	v_mfma_f32_32x32x16_bf16 v[18:33], v[34:37], v[50:53], v[18:33]
	v_mfma_f32_32x32x16_bf16 v[18:33], v[42:45], v[62:65], v[18:33]
	ds_read_b128 v[58:61], v74 offset:0
	ds_read_b128 v[54:57], v75 offset:0
	ds_read_b128 v[50:53], v76 offset:0
	ds_read_b128 v[62:65], v77 offset:0
	s_nop 8
	v_max_f32_e32 v18, 0, v18
	v_max_f32_e32 v19, 0, v19
	v_fma_f32 v18, v174, v18, 0
	v_max_f32_e32 v20, 0, v20
	v_fmac_f32_e32 v18, v173, v19
	v_max_f32_e32 v21, 0, v21
	v_fmac_f32_e32 v18, v172, v20
	v_max_f32_e32 v22, 0, v22
	v_fmac_f32_e32 v18, v171, v21
	v_max_f32_e32 v23, 0, v23
	v_fmac_f32_e32 v18, v170, v22
	v_max_f32_e32 v24, 0, v24
	v_fmac_f32_e32 v18, v169, v23
	v_max_f32_e32 v25, 0, v25
	v_fmac_f32_e32 v18, v168, v24
	v_max_f32_e32 v26, 0, v26
	v_fmac_f32_e32 v18, v167, v25
	v_max_f32_e32 v27, 0, v27
	v_fmac_f32_e32 v18, v166, v26
	v_max_f32_e32 v28, 0, v28
	v_fmac_f32_e32 v18, v165, v27
	v_max_f32_e32 v29, 0, v29
	v_fmac_f32_e32 v18, v164, v28
	v_max_f32_e32 v30, 0, v30
	v_fmac_f32_e32 v18, v163, v29
	v_fmac_f32_e32 v18, v162, v30
	v_max_f32_e32 v19, 0, v31
	v_fmac_f32_e32 v18, v161, v19
	v_max_f32_e32 v19, 0, v32
	v_fmac_f32_e32 v18, v160, v19
	v_max_f32_e32 v19, 0, v33
	v_fmac_f32_e32 v18, v89, v19
	v_not_b32_e32 v19, v18
	v_or_b32_e32 v20, 0x80000000, v18
	v_cmp_gt_i32_e32 vcc, 0, v18
	s_nop 1
	v_cndmask_b32_e32 v18, v20, v19, vcc
	v_cmp_le_u32_e32 vcc, v144, v87
	s_nop 1
	v_cndmask_b32_e32 v243, 0, v18, vcc

.LBB0_600:
	s_or_b64 exec, exec, s[84:85]
	v_mfma_f32_32x32x16_bf16 v[18:33], v[38:41], v[58:61], 0
	v_mfma_f32_32x32x16_bf16 v[18:33], v[46:49], v[54:57], v[18:33]
	v_mfma_f32_32x32x16_bf16 v[18:33], v[34:37], v[50:53], v[18:33]
	v_mfma_f32_32x32x16_bf16 v[18:33], v[42:45], v[62:65], v[18:33]
	ds_read_b128 v[58:61], v74 offset:4096
	ds_read_b128 v[54:57], v75 offset:4096
	ds_read_b128 v[50:53], v76 offset:4096
	ds_read_b128 v[62:65], v77 offset:4096
	s_nop 8
	v_max_f32_e32 v18, 0, v18
	v_max_f32_e32 v19, 0, v19
	v_fma_f32 v18, v174, v18, 0
	v_max_f32_e32 v20, 0, v20
	v_fmac_f32_e32 v18, v173, v19
	v_max_f32_e32 v21, 0, v21
	v_fmac_f32_e32 v18, v172, v20
	v_max_f32_e32 v22, 0, v22
	v_fmac_f32_e32 v18, v171, v21
	v_max_f32_e32 v23, 0, v23
	v_fmac_f32_e32 v18, v170, v22
	v_max_f32_e32 v24, 0, v24
	v_fmac_f32_e32 v18, v169, v23
	v_max_f32_e32 v25, 0, v25
	v_fmac_f32_e32 v18, v168, v24
	v_max_f32_e32 v26, 0, v26
	v_fmac_f32_e32 v18, v167, v25
	v_max_f32_e32 v27, 0, v27
	v_fmac_f32_e32 v18, v166, v26
	v_max_f32_e32 v28, 0, v28
	v_fmac_f32_e32 v18, v165, v27
	v_max_f32_e32 v29, 0, v29
	v_fmac_f32_e32 v18, v164, v28
	v_max_f32_e32 v30, 0, v30
	v_fmac_f32_e32 v18, v163, v29
	v_fmac_f32_e32 v18, v162, v30
	v_max_f32_e32 v19, 0, v31
	v_fmac_f32_e32 v18, v161, v19
	v_max_f32_e32 v19, 0, v32
	v_fmac_f32_e32 v18, v160, v19
	v_max_f32_e32 v19, 0, v33
	v_fmac_f32_e32 v18, v89, v19
	v_not_b32_e32 v19, v18
	v_or_b32_e32 v20, 0x80000000, v18
	v_cmp_gt_i32_e32 vcc, 0, v18
	s_nop 1
	v_cndmask_b32_e32 v18, v20, v19, vcc
	v_cmp_le_u32_e32 vcc, v145, v87
	s_nop 1
	v_cndmask_b32_e32 v244, 0, v18, vcc

.LBB0_604:
	s_or_b64 exec, exec, s[84:85]
	v_mfma_f32_32x32x16_bf16 v[18:33], v[38:41], v[58:61], 0
	v_mfma_f32_32x32x16_bf16 v[18:33], v[46:49], v[54:57], v[18:33]
	v_mfma_f32_32x32x16_bf16 v[18:33], v[34:37], v[50:53], v[18:33]
	v_mfma_f32_32x32x16_bf16 v[18:33], v[42:45], v[62:65], v[18:33]
	ds_read_b128 v[58:61], v74 offset:8192
	ds_read_b128 v[54:57], v75 offset:8192
	ds_read_b128 v[50:53], v76 offset:8192
	ds_read_b128 v[62:65], v77 offset:8192
	s_nop 8
	v_max_f32_e32 v18, 0, v18
	v_max_f32_e32 v19, 0, v19
	v_fma_f32 v18, v174, v18, 0
	v_max_f32_e32 v20, 0, v20
	v_fmac_f32_e32 v18, v173, v19
	v_max_f32_e32 v21, 0, v21
	v_fmac_f32_e32 v18, v172, v20
	v_max_f32_e32 v22, 0, v22
	v_fmac_f32_e32 v18, v171, v21
	v_max_f32_e32 v23, 0, v23
	v_fmac_f32_e32 v18, v170, v22
	v_max_f32_e32 v24, 0, v24
	v_fmac_f32_e32 v18, v169, v23
	v_max_f32_e32 v25, 0, v25
	v_fmac_f32_e32 v18, v168, v24
	v_max_f32_e32 v26, 0, v26
	v_fmac_f32_e32 v18, v167, v25
	v_max_f32_e32 v27, 0, v27
	v_fmac_f32_e32 v18, v166, v26
	v_max_f32_e32 v28, 0, v28
	v_fmac_f32_e32 v18, v165, v27
	v_max_f32_e32 v29, 0, v29
	v_fmac_f32_e32 v18, v164, v28
	v_max_f32_e32 v30, 0, v30
	v_fmac_f32_e32 v18, v163, v29
	v_fmac_f32_e32 v18, v162, v30
	v_max_f32_e32 v19, 0, v31
	v_fmac_f32_e32 v18, v161, v19
	v_max_f32_e32 v19, 0, v32
	v_fmac_f32_e32 v18, v160, v19
	v_max_f32_e32 v19, 0, v33
	v_fmac_f32_e32 v18, v89, v19
	v_not_b32_e32 v19, v18
	v_or_b32_e32 v20, 0x80000000, v18
	v_cmp_gt_i32_e32 vcc, 0, v18
	s_nop 1
	v_cndmask_b32_e32 v18, v20, v19, vcc
	v_cmp_le_u32_e32 vcc, v146, v87
	s_nop 1
	v_cndmask_b32_e32 v245, 0, v18, vcc

.LBB0_608:
	s_or_b64 exec, exec, s[84:85]
	v_mfma_f32_32x32x16_bf16 v[18:33], v[38:41], v[58:61], 0
	v_mfma_f32_32x32x16_bf16 v[18:33], v[46:49], v[54:57], v[18:33]
	v_mfma_f32_32x32x16_bf16 v[18:33], v[34:37], v[50:53], v[18:33]
	v_mfma_f32_32x32x16_bf16 v[18:33], v[42:45], v[62:65], v[18:33]
	ds_read_b128 v[58:61], v74 offset:12288
	ds_read_b128 v[54:57], v75 offset:12288
	ds_read_b128 v[50:53], v76 offset:12288
	ds_read_b128 v[62:65], v77 offset:12288
	s_nop 8
	v_max_f32_e32 v18, 0, v18
	v_max_f32_e32 v19, 0, v19
	v_fma_f32 v18, v174, v18, 0
	v_max_f32_e32 v20, 0, v20
	v_fmac_f32_e32 v18, v173, v19
	v_max_f32_e32 v21, 0, v21
	v_fmac_f32_e32 v18, v172, v20
	v_max_f32_e32 v22, 0, v22
	v_fmac_f32_e32 v18, v171, v21
	v_max_f32_e32 v23, 0, v23
	v_fmac_f32_e32 v18, v170, v22
	v_max_f32_e32 v24, 0, v24
	v_fmac_f32_e32 v18, v169, v23
	v_max_f32_e32 v25, 0, v25
	v_fmac_f32_e32 v18, v168, v24
	v_max_f32_e32 v26, 0, v26
	v_fmac_f32_e32 v18, v167, v25
	v_max_f32_e32 v27, 0, v27
	v_fmac_f32_e32 v18, v166, v26
	v_max_f32_e32 v28, 0, v28
	v_fmac_f32_e32 v18, v165, v27
	v_max_f32_e32 v29, 0, v29
	v_fmac_f32_e32 v18, v164, v28
	v_max_f32_e32 v30, 0, v30
	v_fmac_f32_e32 v18, v163, v29
	v_fmac_f32_e32 v18, v162, v30
	v_max_f32_e32 v19, 0, v31
	v_fmac_f32_e32 v18, v161, v19
	v_max_f32_e32 v19, 0, v32
	v_fmac_f32_e32 v18, v160, v19
	v_max_f32_e32 v19, 0, v33
	v_fmac_f32_e32 v18, v89, v19
	v_not_b32_e32 v19, v18
	v_or_b32_e32 v20, 0x80000000, v18
	v_cmp_gt_i32_e32 vcc, 0, v18
	s_nop 1
	v_cndmask_b32_e32 v18, v20, v19, vcc
	v_cmp_le_u32_e32 vcc, v147, v87
	s_nop 1
	v_cndmask_b32_e32 v246, 0, v18, vcc

.LBB0_612:
	s_or_b64 exec, exec, s[84:85]
	v_mfma_f32_32x32x16_bf16 v[18:33], v[38:41], v[58:61], 0
	v_mfma_f32_32x32x16_bf16 v[18:33], v[46:49], v[54:57], v[18:33]
	v_mfma_f32_32x32x16_bf16 v[18:33], v[34:37], v[50:53], v[18:33]
	v_mfma_f32_32x32x16_bf16 v[18:33], v[42:45], v[62:65], v[18:33]
	ds_read_b128 v[58:61], v74 offset:16384
	ds_read_b128 v[54:57], v75 offset:16384
	ds_read_b128 v[50:53], v76 offset:16384
	ds_read_b128 v[62:65], v77 offset:16384
	s_nop 8
	v_max_f32_e32 v18, 0, v18
	v_max_f32_e32 v19, 0, v19
	v_fma_f32 v18, v174, v18, 0
	v_max_f32_e32 v20, 0, v20
	v_fmac_f32_e32 v18, v173, v19
	v_max_f32_e32 v21, 0, v21
	v_fmac_f32_e32 v18, v172, v20
	v_max_f32_e32 v22, 0, v22
	v_fmac_f32_e32 v18, v171, v21
	v_max_f32_e32 v23, 0, v23
	v_fmac_f32_e32 v18, v170, v22
	v_max_f32_e32 v24, 0, v24
	v_fmac_f32_e32 v18, v169, v23
	v_max_f32_e32 v25, 0, v25
	v_fmac_f32_e32 v18, v168, v24
	v_max_f32_e32 v26, 0, v26
	v_fmac_f32_e32 v18, v167, v25
	v_max_f32_e32 v27, 0, v27
	v_fmac_f32_e32 v18, v166, v26
	v_max_f32_e32 v28, 0, v28
	v_fmac_f32_e32 v18, v165, v27
	v_max_f32_e32 v29, 0, v29
	v_fmac_f32_e32 v18, v164, v28
	v_max_f32_e32 v30, 0, v30
	v_fmac_f32_e32 v18, v163, v29
	v_fmac_f32_e32 v18, v162, v30
	v_max_f32_e32 v19, 0, v31
	v_fmac_f32_e32 v18, v161, v19
	v_max_f32_e32 v19, 0, v32
	v_fmac_f32_e32 v18, v160, v19
	v_max_f32_e32 v19, 0, v33
	v_fmac_f32_e32 v18, v89, v19
	v_not_b32_e32 v19, v18
	v_or_b32_e32 v20, 0x80000000, v18
	v_cmp_gt_i32_e32 vcc, 0, v18
	s_nop 1
	v_cndmask_b32_e32 v18, v20, v19, vcc
	v_cmp_le_u32_e32 vcc, v148, v87
	s_nop 1
	v_cndmask_b32_e32 v247, 0, v18, vcc

.LBB0_616:
	s_or_b64 exec, exec, s[84:85]
	v_mfma_f32_32x32x16_bf16 v[18:33], v[38:41], v[58:61], 0
	v_mfma_f32_32x32x16_bf16 v[18:33], v[46:49], v[54:57], v[18:33]
	v_mfma_f32_32x32x16_bf16 v[18:33], v[34:37], v[50:53], v[18:33]
	v_mfma_f32_32x32x16_bf16 v[18:33], v[42:45], v[62:65], v[18:33]
	ds_read_b128 v[58:61], v74 offset:20480
	ds_read_b128 v[54:57], v75 offset:20480
	ds_read_b128 v[50:53], v76 offset:20480
	ds_read_b128 v[62:65], v77 offset:20480
	s_nop 8
	v_max_f32_e32 v18, 0, v18
	v_max_f32_e32 v19, 0, v19
	v_fma_f32 v18, v174, v18, 0
	v_max_f32_e32 v20, 0, v20
	v_fmac_f32_e32 v18, v173, v19
	v_max_f32_e32 v21, 0, v21
	v_fmac_f32_e32 v18, v172, v20
	v_max_f32_e32 v22, 0, v22
	v_fmac_f32_e32 v18, v171, v21
	v_max_f32_e32 v23, 0, v23
	v_fmac_f32_e32 v18, v170, v22
	v_max_f32_e32 v24, 0, v24
	v_fmac_f32_e32 v18, v169, v23
	v_max_f32_e32 v25, 0, v25
	v_fmac_f32_e32 v18, v168, v24
	v_max_f32_e32 v26, 0, v26
	v_fmac_f32_e32 v18, v167, v25
	v_max_f32_e32 v27, 0, v27
	v_fmac_f32_e32 v18, v166, v26
	v_max_f32_e32 v28, 0, v28
	v_fmac_f32_e32 v18, v165, v27
	v_max_f32_e32 v29, 0, v29
	v_fmac_f32_e32 v18, v164, v28
	v_max_f32_e32 v30, 0, v30
	v_fmac_f32_e32 v18, v163, v29
	v_fmac_f32_e32 v18, v162, v30
	v_max_f32_e32 v19, 0, v31
	v_fmac_f32_e32 v18, v161, v19
	v_max_f32_e32 v19, 0, v32
	v_fmac_f32_e32 v18, v160, v19
	v_max_f32_e32 v19, 0, v33
	v_fmac_f32_e32 v18, v89, v19
	v_not_b32_e32 v19, v18
	v_or_b32_e32 v20, 0x80000000, v18
	v_cmp_gt_i32_e32 vcc, 0, v18
	s_nop 1
	v_cndmask_b32_e32 v18, v20, v19, vcc
	v_cmp_le_u32_e32 vcc, v149, v87
	s_nop 1
	v_cndmask_b32_e32 v248, 0, v18, vcc

.LBB0_620:
	s_or_b64 exec, exec, s[84:85]
	v_mfma_f32_32x32x16_bf16 v[18:33], v[38:41], v[58:61], 0
	v_mfma_f32_32x32x16_bf16 v[18:33], v[46:49], v[54:57], v[18:33]
	v_mfma_f32_32x32x16_bf16 v[18:33], v[34:37], v[50:53], v[18:33]
	v_mfma_f32_32x32x16_bf16 v[18:33], v[42:45], v[62:65], v[18:33]
	ds_read_b128 v[58:61], v74 offset:24576
	ds_read_b128 v[54:57], v75 offset:24576
	ds_read_b128 v[50:53], v76 offset:24576
	ds_read_b128 v[62:65], v77 offset:24576
	s_nop 8
	v_max_f32_e32 v18, 0, v18
	v_max_f32_e32 v19, 0, v19
	v_fma_f32 v18, v174, v18, 0
	v_max_f32_e32 v20, 0, v20
	v_fmac_f32_e32 v18, v173, v19
	v_max_f32_e32 v21, 0, v21
	v_fmac_f32_e32 v18, v172, v20
	v_max_f32_e32 v22, 0, v22
	v_fmac_f32_e32 v18, v171, v21
	v_max_f32_e32 v23, 0, v23
	v_fmac_f32_e32 v18, v170, v22
	v_max_f32_e32 v24, 0, v24
	v_fmac_f32_e32 v18, v169, v23
	v_max_f32_e32 v25, 0, v25
	v_fmac_f32_e32 v18, v168, v24
	v_max_f32_e32 v26, 0, v26
	v_fmac_f32_e32 v18, v167, v25
	v_max_f32_e32 v27, 0, v27
	v_fmac_f32_e32 v18, v166, v26
	v_max_f32_e32 v28, 0, v28
	v_fmac_f32_e32 v18, v165, v27
	v_max_f32_e32 v29, 0, v29
	v_fmac_f32_e32 v18, v164, v28
	v_max_f32_e32 v30, 0, v30
	v_fmac_f32_e32 v18, v163, v29
	v_fmac_f32_e32 v18, v162, v30
	v_max_f32_e32 v19, 0, v31
	v_fmac_f32_e32 v18, v161, v19
	v_max_f32_e32 v19, 0, v32
	v_fmac_f32_e32 v18, v160, v19
	v_max_f32_e32 v19, 0, v33
	v_fmac_f32_e32 v18, v89, v19
	v_not_b32_e32 v19, v18
	v_or_b32_e32 v20, 0x80000000, v18
	v_cmp_gt_i32_e32 vcc, 0, v18
	s_nop 1
	v_cndmask_b32_e32 v18, v20, v19, vcc
	v_cmp_le_u32_e32 vcc, v150, v87
	s_nop 1
	v_cndmask_b32_e32 v249, 0, v18, vcc

.LBB0_624:
	s_or_b64 exec, exec, s[84:85]
	v_mfma_f32_32x32x16_bf16 v[18:33], v[38:41], v[58:61], 0
	v_mfma_f32_32x32x16_bf16 v[18:33], v[46:49], v[54:57], v[18:33]
	v_mfma_f32_32x32x16_bf16 v[18:33], v[34:37], v[50:53], v[18:33]
	v_mfma_f32_32x32x16_bf16 v[18:33], v[42:45], v[62:65], v[18:33]
	ds_read_b128 v[58:61], v74 offset:28672
	ds_read_b128 v[54:57], v75 offset:28672
	ds_read_b128 v[50:53], v76 offset:28672
	ds_read_b128 v[62:65], v77 offset:28672
	s_nop 8
	v_max_f32_e32 v18, 0, v18
	v_max_f32_e32 v19, 0, v19
	v_fma_f32 v18, v174, v18, 0
	v_max_f32_e32 v20, 0, v20
	v_fmac_f32_e32 v18, v173, v19
	v_max_f32_e32 v21, 0, v21
	v_fmac_f32_e32 v18, v172, v20
	v_max_f32_e32 v22, 0, v22
	v_fmac_f32_e32 v18, v171, v21
	v_max_f32_e32 v23, 0, v23
	v_fmac_f32_e32 v18, v170, v22
	v_max_f32_e32 v24, 0, v24
	v_fmac_f32_e32 v18, v169, v23
	v_max_f32_e32 v25, 0, v25
	v_fmac_f32_e32 v18, v168, v24
	v_max_f32_e32 v26, 0, v26
	v_fmac_f32_e32 v18, v167, v25
	v_max_f32_e32 v27, 0, v27
	v_fmac_f32_e32 v18, v166, v26
	v_max_f32_e32 v28, 0, v28
	v_fmac_f32_e32 v18, v165, v27
	v_max_f32_e32 v29, 0, v29
	v_fmac_f32_e32 v18, v164, v28
	v_max_f32_e32 v30, 0, v30
	v_fmac_f32_e32 v18, v163, v29
	v_fmac_f32_e32 v18, v162, v30
	v_max_f32_e32 v19, 0, v31
	v_fmac_f32_e32 v18, v161, v19
	v_max_f32_e32 v19, 0, v32
	v_fmac_f32_e32 v18, v160, v19
	v_max_f32_e32 v19, 0, v33
	v_fmac_f32_e32 v18, v89, v19
	v_not_b32_e32 v19, v18
	v_or_b32_e32 v20, 0x80000000, v18
	v_cmp_gt_i32_e32 vcc, 0, v18
	s_nop 1
	v_cndmask_b32_e32 v18, v20, v19, vcc
	v_cmp_le_u32_e32 vcc, v151, v87
	s_nop 1
	v_cndmask_b32_e32 v250, 0, v18, vcc
.LBB0_625:
	s_or_b64 exec, exec, s[82:83]
	s_movk_i32 s2, 0x71f
	v_cmp_lt_u32_e32 vcc, s2, v177
	v_mov_b32_e32 v199, 0
	s_and_saveexec_b64 s[82:83], vcc
	s_cbranch_execz .LBB0_629
	s_movk_i32 s2, 0x73f
	s_waitcnt lgkmcnt(0)
	s_waitcnt vmcnt(0)
	s_barrier
	v_cmp_lt_u32_e32 vcc, s2, v177
	s_and_saveexec_b64 s[84:85], vcc
	s_cbranch_execz .LBB0_628
.LBB0_628:
	s_or_b64 exec, exec, s[84:85]
	v_mfma_f32_32x32x16_bf16 v[18:33], v[38:41], v[58:61], 0
	v_mfma_f32_32x32x16_bf16 v[18:33], v[46:49], v[54:57], v[18:33]
	v_mfma_f32_32x32x16_bf16 v[18:33], v[34:37], v[50:53], v[18:33]
	v_mfma_f32_32x32x16_bf16 v[18:33], v[42:45], v[62:65], v[18:33]
	ds_read_b128 v[58:61], v74 offset:32768
	ds_read_b128 v[54:57], v75 offset:32768
	ds_read_b128 v[50:53], v76 offset:32768
	ds_read_b128 v[62:65], v77 offset:32768
	s_nop 8
	v_max_f32_e32 v18, 0, v18
	v_max_f32_e32 v19, 0, v19
	v_fma_f32 v18, v174, v18, 0
	v_max_f32_e32 v20, 0, v20
	v_fmac_f32_e32 v18, v173, v19
	v_max_f32_e32 v21, 0, v21
	v_fmac_f32_e32 v18, v172, v20
	v_max_f32_e32 v22, 0, v22
	v_fmac_f32_e32 v18, v171, v21
	v_max_f32_e32 v23, 0, v23
	v_fmac_f32_e32 v18, v170, v22
	v_max_f32_e32 v24, 0, v24
	v_fmac_f32_e32 v18, v169, v23
	v_max_f32_e32 v25, 0, v25
	v_fmac_f32_e32 v18, v168, v24
	v_max_f32_e32 v26, 0, v26
	v_fmac_f32_e32 v18, v167, v25
	v_max_f32_e32 v27, 0, v27
	v_fmac_f32_e32 v18, v166, v26
	v_max_f32_e32 v28, 0, v28
	v_fmac_f32_e32 v18, v165, v27
	v_max_f32_e32 v29, 0, v29
	v_fmac_f32_e32 v18, v164, v28
	v_max_f32_e32 v30, 0, v30
	v_fmac_f32_e32 v18, v163, v29
	v_fmac_f32_e32 v18, v162, v30
	v_max_f32_e32 v19, 0, v31
	v_fmac_f32_e32 v18, v161, v19
	v_max_f32_e32 v19, 0, v32
	v_fmac_f32_e32 v18, v160, v19
	v_max_f32_e32 v19, 0, v33
	v_fmac_f32_e32 v18, v89, v19
	v_not_b32_e32 v19, v18
	v_or_b32_e32 v20, 0x80000000, v18
	v_cmp_gt_i32_e32 vcc, 0, v18
	s_nop 1
	v_cndmask_b32_e32 v18, v20, v19, vcc
	v_cmp_le_u32_e32 vcc, v152, v87
	s_nop 1
	v_cndmask_b32_e32 v199, 0, v18, vcc

.LBB0_632:
	s_or_b64 exec, exec, s[84:85]
	v_mfma_f32_32x32x16_bf16 v[18:33], v[38:41], v[58:61], 0
	v_mfma_f32_32x32x16_bf16 v[18:33], v[46:49], v[54:57], v[18:33]
	v_mfma_f32_32x32x16_bf16 v[18:33], v[34:37], v[50:53], v[18:33]
	v_mfma_f32_32x32x16_bf16 v[18:33], v[42:45], v[62:65], v[18:33]
	ds_read_b128 v[58:61], v74 offset:36864
	ds_read_b128 v[54:57], v75 offset:36864
	ds_read_b128 v[50:53], v76 offset:36864
	ds_read_b128 v[62:65], v77 offset:36864
	s_nop 8
	v_max_f32_e32 v18, 0, v18
	v_max_f32_e32 v19, 0, v19
	v_fma_f32 v18, v174, v18, 0
	v_max_f32_e32 v20, 0, v20
	v_fmac_f32_e32 v18, v173, v19
	v_max_f32_e32 v21, 0, v21
	v_fmac_f32_e32 v18, v172, v20
	v_max_f32_e32 v22, 0, v22
	v_fmac_f32_e32 v18, v171, v21
	v_max_f32_e32 v23, 0, v23
	v_fmac_f32_e32 v18, v170, v22
	v_max_f32_e32 v24, 0, v24
	v_fmac_f32_e32 v18, v169, v23
	v_max_f32_e32 v25, 0, v25
	v_fmac_f32_e32 v18, v168, v24
	v_max_f32_e32 v26, 0, v26
	v_fmac_f32_e32 v18, v167, v25
	v_max_f32_e32 v27, 0, v27
	v_fmac_f32_e32 v18, v166, v26
	v_max_f32_e32 v28, 0, v28
	v_fmac_f32_e32 v18, v165, v27
	v_max_f32_e32 v29, 0, v29
	v_fmac_f32_e32 v18, v164, v28
	v_max_f32_e32 v30, 0, v30
	v_fmac_f32_e32 v18, v163, v29
	v_fmac_f32_e32 v18, v162, v30
	v_max_f32_e32 v19, 0, v31
	v_fmac_f32_e32 v18, v161, v19
	v_max_f32_e32 v19, 0, v32
	v_fmac_f32_e32 v18, v160, v19
	v_max_f32_e32 v19, 0, v33
	v_fmac_f32_e32 v18, v89, v19
	v_not_b32_e32 v19, v18
	v_or_b32_e32 v20, 0x80000000, v18
	v_cmp_gt_i32_e32 vcc, 0, v18
	s_nop 1
	v_cndmask_b32_e32 v18, v20, v19, vcc
	v_cmp_le_u32_e32 vcc, v153, v87
	s_nop 1
	v_cndmask_b32_e32 v200, 0, v18, vcc

.LBB0_636:
	s_or_b64 exec, exec, s[84:85]
	v_mfma_f32_32x32x16_bf16 v[18:33], v[38:41], v[58:61], 0
	v_mfma_f32_32x32x16_bf16 v[18:33], v[46:49], v[54:57], v[18:33]
	v_mfma_f32_32x32x16_bf16 v[18:33], v[34:37], v[50:53], v[18:33]
	v_mfma_f32_32x32x16_bf16 v[18:33], v[42:45], v[62:65], v[18:33]
	ds_read_b128 v[58:61], v74 offset:40960
	ds_read_b128 v[54:57], v75 offset:40960
	ds_read_b128 v[50:53], v76 offset:40960
	ds_read_b128 v[62:65], v77 offset:40960
	s_nop 8
	v_max_f32_e32 v18, 0, v18
	v_max_f32_e32 v19, 0, v19
	v_fma_f32 v18, v174, v18, 0
	v_max_f32_e32 v20, 0, v20
	v_fmac_f32_e32 v18, v173, v19
	v_max_f32_e32 v21, 0, v21
	v_fmac_f32_e32 v18, v172, v20
	v_max_f32_e32 v22, 0, v22
	v_fmac_f32_e32 v18, v171, v21
	v_max_f32_e32 v23, 0, v23
	v_fmac_f32_e32 v18, v170, v22
	v_max_f32_e32 v24, 0, v24
	v_fmac_f32_e32 v18, v169, v23
	v_max_f32_e32 v25, 0, v25
	v_fmac_f32_e32 v18, v168, v24
	v_max_f32_e32 v26, 0, v26
	v_fmac_f32_e32 v18, v167, v25
	v_max_f32_e32 v27, 0, v27
	v_fmac_f32_e32 v18, v166, v26
	v_max_f32_e32 v28, 0, v28
	v_fmac_f32_e32 v18, v165, v27
	v_max_f32_e32 v29, 0, v29
	v_fmac_f32_e32 v18, v164, v28
	v_max_f32_e32 v30, 0, v30
	v_fmac_f32_e32 v18, v163, v29
	v_fmac_f32_e32 v18, v162, v30
	v_max_f32_e32 v19, 0, v31
	v_fmac_f32_e32 v18, v161, v19
	v_max_f32_e32 v19, 0, v32
	v_fmac_f32_e32 v18, v160, v19
	v_max_f32_e32 v19, 0, v33
	v_fmac_f32_e32 v18, v89, v19
	v_not_b32_e32 v19, v18
	v_or_b32_e32 v20, 0x80000000, v18
	v_cmp_gt_i32_e32 vcc, 0, v18
	s_nop 1
	v_cndmask_b32_e32 v18, v20, v19, vcc
	v_cmp_le_u32_e32 vcc, v154, v87
	s_nop 1
	v_cndmask_b32_e32 v207, 0, v18, vcc

.LBB0_640:
	s_or_b64 exec, exec, s[84:85]
	v_mfma_f32_32x32x16_bf16 v[18:33], v[38:41], v[58:61], 0
	v_mfma_f32_32x32x16_bf16 v[18:33], v[46:49], v[54:57], v[18:33]
	v_mfma_f32_32x32x16_bf16 v[18:33], v[34:37], v[50:53], v[18:33]
	v_mfma_f32_32x32x16_bf16 v[18:33], v[42:45], v[62:65], v[18:33]
	ds_read_b128 v[58:61], v74 offset:45056
	ds_read_b128 v[54:57], v75 offset:45056
	ds_read_b128 v[50:53], v76 offset:45056
	ds_read_b128 v[62:65], v77 offset:45056
	s_nop 8
	v_max_f32_e32 v18, 0, v18
	v_max_f32_e32 v19, 0, v19
	v_fma_f32 v18, v174, v18, 0
	v_max_f32_e32 v20, 0, v20
	v_fmac_f32_e32 v18, v173, v19
	v_max_f32_e32 v21, 0, v21
	v_fmac_f32_e32 v18, v172, v20
	v_max_f32_e32 v22, 0, v22
	v_fmac_f32_e32 v18, v171, v21
	v_max_f32_e32 v23, 0, v23
	v_fmac_f32_e32 v18, v170, v22
	v_max_f32_e32 v24, 0, v24
	v_fmac_f32_e32 v18, v169, v23
	v_max_f32_e32 v25, 0, v25
	v_fmac_f32_e32 v18, v168, v24
	v_max_f32_e32 v26, 0, v26
	v_fmac_f32_e32 v18, v167, v25
	v_max_f32_e32 v27, 0, v27
	v_fmac_f32_e32 v18, v166, v26
	v_max_f32_e32 v28, 0, v28
	v_fmac_f32_e32 v18, v165, v27
	v_max_f32_e32 v29, 0, v29
	v_fmac_f32_e32 v18, v164, v28
	v_max_f32_e32 v30, 0, v30
	v_fmac_f32_e32 v18, v163, v29
	v_fmac_f32_e32 v18, v162, v30
	v_max_f32_e32 v19, 0, v31
	v_fmac_f32_e32 v18, v161, v19
	v_max_f32_e32 v19, 0, v32
	v_fmac_f32_e32 v18, v160, v19
	v_max_f32_e32 v19, 0, v33
	v_fmac_f32_e32 v18, v89, v19
	v_not_b32_e32 v19, v18
	v_or_b32_e32 v20, 0x80000000, v18
	v_cmp_gt_i32_e32 vcc, 0, v18
	s_nop 1
	v_cndmask_b32_e32 v18, v20, v19, vcc
	v_cmp_le_u32_e32 vcc, v155, v87
	s_nop 1
	v_cndmask_b32_e32 v208, 0, v18, vcc

.LBB0_644:
	s_or_b64 exec, exec, s[84:85]
	v_mfma_f32_32x32x16_bf16 v[18:33], v[38:41], v[58:61], 0
	v_mfma_f32_32x32x16_bf16 v[18:33], v[46:49], v[54:57], v[18:33]
	v_mfma_f32_32x32x16_bf16 v[18:33], v[34:37], v[50:53], v[18:33]
	v_mfma_f32_32x32x16_bf16 v[18:33], v[42:45], v[62:65], v[18:33]
	ds_read_b128 v[58:61], v74 offset:49152
	ds_read_b128 v[54:57], v75 offset:49152
	ds_read_b128 v[50:53], v76 offset:49152
	ds_read_b128 v[62:65], v77 offset:49152
	s_nop 8
	v_max_f32_e32 v18, 0, v18
	v_max_f32_e32 v19, 0, v19
	v_fma_f32 v18, v174, v18, 0
	v_max_f32_e32 v20, 0, v20
	v_fmac_f32_e32 v18, v173, v19
	v_max_f32_e32 v21, 0, v21
	v_fmac_f32_e32 v18, v172, v20
	v_max_f32_e32 v22, 0, v22
	v_fmac_f32_e32 v18, v171, v21
	v_max_f32_e32 v23, 0, v23
	v_fmac_f32_e32 v18, v170, v22
	v_max_f32_e32 v24, 0, v24
	v_fmac_f32_e32 v18, v169, v23
	v_max_f32_e32 v25, 0, v25
	v_fmac_f32_e32 v18, v168, v24
	v_max_f32_e32 v26, 0, v26
	v_fmac_f32_e32 v18, v167, v25
	v_max_f32_e32 v27, 0, v27
	v_fmac_f32_e32 v18, v166, v26
	v_max_f32_e32 v28, 0, v28
	v_fmac_f32_e32 v18, v165, v27
	v_max_f32_e32 v29, 0, v29
	v_fmac_f32_e32 v18, v164, v28
	v_max_f32_e32 v30, 0, v30
	v_fmac_f32_e32 v18, v163, v29
	v_fmac_f32_e32 v18, v162, v30
	v_max_f32_e32 v19, 0, v31
	v_fmac_f32_e32 v18, v161, v19
	v_max_f32_e32 v19, 0, v32
	v_fmac_f32_e32 v18, v160, v19
	v_max_f32_e32 v19, 0, v33
	v_fmac_f32_e32 v18, v89, v19
	v_not_b32_e32 v19, v18
	v_or_b32_e32 v20, 0x80000000, v18
	v_cmp_gt_i32_e32 vcc, 0, v18
	s_nop 1
	v_cndmask_b32_e32 v18, v20, v19, vcc
	v_cmp_le_u32_e32 vcc, v156, v87
	s_nop 1
	v_cndmask_b32_e32 v210, 0, v18, vcc

.LBB0_648:
	s_or_b64 exec, exec, s[84:85]
	v_mfma_f32_32x32x16_bf16 v[18:33], v[38:41], v[58:61], 0
	v_mfma_f32_32x32x16_bf16 v[18:33], v[46:49], v[54:57], v[18:33]
	v_mfma_f32_32x32x16_bf16 v[18:33], v[34:37], v[50:53], v[18:33]
	v_mfma_f32_32x32x16_bf16 v[18:33], v[42:45], v[62:65], v[18:33]
	ds_read_b128 v[58:61], v74 offset:53248
	ds_read_b128 v[54:57], v75 offset:53248
	ds_read_b128 v[50:53], v76 offset:53248
	ds_read_b128 v[62:65], v77 offset:53248
	s_nop 8
	v_max_f32_e32 v18, 0, v18
	v_max_f32_e32 v19, 0, v19
	v_fma_f32 v18, v174, v18, 0
	v_max_f32_e32 v20, 0, v20
	v_fmac_f32_e32 v18, v173, v19
	v_max_f32_e32 v21, 0, v21
	v_fmac_f32_e32 v18, v172, v20
	v_max_f32_e32 v22, 0, v22
	v_fmac_f32_e32 v18, v171, v21
	v_max_f32_e32 v23, 0, v23
	v_fmac_f32_e32 v18, v170, v22
	v_max_f32_e32 v24, 0, v24
	v_fmac_f32_e32 v18, v169, v23
	v_max_f32_e32 v25, 0, v25
	v_fmac_f32_e32 v18, v168, v24
	v_max_f32_e32 v26, 0, v26
	v_fmac_f32_e32 v18, v167, v25
	v_max_f32_e32 v27, 0, v27
	v_fmac_f32_e32 v18, v166, v26
	v_max_f32_e32 v28, 0, v28
	v_fmac_f32_e32 v18, v165, v27
	v_max_f32_e32 v29, 0, v29
	v_fmac_f32_e32 v18, v164, v28
	v_max_f32_e32 v30, 0, v30
	v_fmac_f32_e32 v18, v163, v29
	v_fmac_f32_e32 v18, v162, v30
	v_max_f32_e32 v19, 0, v31
	v_fmac_f32_e32 v18, v161, v19
	v_max_f32_e32 v19, 0, v32
	v_fmac_f32_e32 v18, v160, v19
	v_max_f32_e32 v19, 0, v33
	v_fmac_f32_e32 v18, v89, v19
	v_not_b32_e32 v19, v18
	v_or_b32_e32 v20, 0x80000000, v18
	v_cmp_gt_i32_e32 vcc, 0, v18
	s_nop 1
	v_cndmask_b32_e32 v18, v20, v19, vcc
	v_cmp_le_u32_e32 vcc, v157, v87
	s_nop 1
	v_cndmask_b32_e32 v70, 0, v18, vcc
